# hand-written prep phase: all tile loads in flight, ring-of-3 row loads, nt (streaming) hint on once-read f32 inputs
# speedup vs baseline: 1.0514x; 1.0514x over previous
.LBB0_5:
	s_or_b64 exec, exec, s[4:5]
	v_and_b32_e32 v2, 63, v0
	v_lshrrev_b32_e32 v16, 6, v0
	s_load_dword s3, s[0:1], 0xf0
	s_mov_b32 s100, 0
	s_mov_b32 s101, 0
	s_waitcnt lgkmcnt(0)
	s_cmpk_eq_u32 s3, 0x100
	s_cbranch_scc0 .Lprep_old
.Lprep_new:
	s_load_dwordx4 s[4:7], s[0:1], 0x0
	s_load_dwordx4 s[8:11], s[0:1], 0x10
	s_load_dwordx4 s[12:15], s[0:1], 0x48
	s_load_dwordx2 s[16:17], s[0:1], 0x68
	s_load_dwordx4 s[20:23], s[0:1], 0x78
	s_load_dwordx2 s[24:25], s[0:1], 0x88
	s_load_dwordx4 s[28:31], s[0:1], 0x98
	v_readfirstlane_b32 s32, v16
	v_lshrrev_b32_e32 v3, 4, v0
	v_and_b32_e32 v4, 15, v0
	v_lshlrev_b32_e32 v4, 4, v4
	v_lshlrev_b32_e32 v6, 4, v2
	v_lshlrev_b32_e32 v11, 3, v2
	s_lshl_b32 s33, s2, 3
	s_add_u32 s33, s33, s32
	s_cmpk_lt_u32 s2, 0x80
	s_cselect_b32 s34, 0, 0x180
	s_add_u32 s34, s34, s2
	s_cmpk_lt_u32 s2, 0xc0
	s_cselect_b32 s35, 6, 5
	s_cmpk_lt_u32 s2, 0x80
	s_cselect_b32 s92, 4, s35
	s_waitcnt lgkmcnt(0)
	s_add_u32 s36, s34, 0
	s_cmpk_lt_u32 s36, 0x340
	s_cbranch_scc1 .Lprep_cin_0
	s_cmpk_lt_u32 s36, 0x440
	s_cbranch_scc1 .Lprep_cout_0
	s_sub_u32 s37, s36, 0x440
	s_lshr_b32 s38, s37, 3
	s_and_b32 s39, s37, 7
	s_mov_b32 s40, 0x800
	s_mov_b64 s[42:43], s[14:15]
	s_mov_b64 s[48:49], s[12:13]
	s_mov_b64 s[50:51], s[24:25]
	s_mov_b32 s86, 0
	s_branch .Lprep_cdone_0
.Lprep_cout_0:
	s_sub_u32 s37, s36, 0x340
	s_lshr_b32 s38, s37, 4
	s_and_b32 s39, s37, 15
	s_mov_b32 s40, 0x1000
	s_mov_b64 s[42:43], s[16:17]
	s_mov_b64 s[48:49], s[8:9]
	s_mov_b64 s[50:51], s[22:23]
	s_mov_b32 s86, 1
	s_branch .Lprep_cdone_0
.Lprep_cin_0:
	s_mul_i32 s38, s36, 0x4ed
	s_lshr_b32 s38, s38, 16
	s_mul_i32 s39, s38, 52
	s_sub_u32 s39, s36, s39
	s_and_b32 s41, s39, -2
	s_add_u32 s37, s39, 6
	s_cmp_eq_u32 s41, 2
	s_cselect_b32 s37, s37, s39
	s_sub_u32 s52, s39, 6
	s_cmp_eq_u32 s41, 8
	s_cselect_b32 s37, s52, s37
	s_mov_b32 s40, 0x3400
	s_mov_b64 s[42:43], s[10:11]
	s_mov_b64 s[48:49], s[8:9]
	s_mov_b64 s[50:51], s[20:21]
	s_mov_b32 s86, 0
	s_mov_b32 s53, s39
	s_mov_b32 s39, s37
	s_mov_b32 s37, s53
	s_branch .Lprep_cjoin_0
.Lprep_cdone_0:
	s_mov_b32 s37, s39
.Lprep_cjoin_0:
	s_lshl_b32 s41, s38, 6
	s_mul_i32 s41, s41, s40
	s_lshl_b32 s52, s37, 8
	s_add_u32 s41, s41, s52
	s_add_u32 s42, s42, s41
	s_addc_u32 s43, s43, 0
	s_lshl_b32 s52, s40, 5
	s_add_u32 s54, s42, s52
	s_addc_u32 s55, s43, 0
	v_mad_u32_u24 v5, v3, s40, v4
	s_lshl_b32 s52, s38, 8
	s_add_u32 s48, s48, s52
	s_addc_u32 s49, s49, 0
	s_lshl_b32 s52, s39, 17
	s_lshl_b32 s53, s38, 7
	s_add_u32 s52, s52, s53
	s_add_u32 s74, s50, s52
	s_addc_u32 s75, s51, 0
	global_load_dwordx4 v[20:23], v5, s[42:43] nt
	global_load_dwordx4 v[24:27], v5, s[54:55] nt
	global_load_dwordx4 v[68:71], v4, s[48:49]
	s_add_u32 s36, s34, 128
	s_cmpk_lt_u32 s36, 0x340
	s_cbranch_scc1 .Lprep_cin_1
	s_cmpk_lt_u32 s36, 0x440
	s_cbranch_scc1 .Lprep_cout_1
	s_sub_u32 s37, s36, 0x440
	s_lshr_b32 s38, s37, 3
	s_and_b32 s39, s37, 7
	s_mov_b32 s40, 0x800
	s_mov_b64 s[42:43], s[14:15]
	s_mov_b64 s[48:49], s[12:13]
	s_mov_b64 s[50:51], s[24:25]
	s_mov_b32 s87, 0
	s_branch .Lprep_cdone_1
.Lprep_cout_1:
	s_sub_u32 s37, s36, 0x340
	s_lshr_b32 s38, s37, 4
	s_and_b32 s39, s37, 15
	s_mov_b32 s40, 0x1000
	s_mov_b64 s[42:43], s[16:17]
	s_mov_b64 s[48:49], s[8:9]
	s_mov_b64 s[50:51], s[22:23]
	s_mov_b32 s87, 1
	s_branch .Lprep_cdone_1
.Lprep_cin_1:
	s_mul_i32 s38, s36, 0x4ed
	s_lshr_b32 s38, s38, 16
	s_mul_i32 s39, s38, 52
	s_sub_u32 s39, s36, s39
	s_and_b32 s41, s39, -2
	s_add_u32 s37, s39, 6
	s_cmp_eq_u32 s41, 2
	s_cselect_b32 s37, s37, s39
	s_sub_u32 s52, s39, 6
	s_cmp_eq_u32 s41, 8
	s_cselect_b32 s37, s52, s37
	s_mov_b32 s40, 0x3400
	s_mov_b64 s[42:43], s[10:11]
	s_mov_b64 s[48:49], s[8:9]
	s_mov_b64 s[50:51], s[20:21]
	s_mov_b32 s87, 0
	s_mov_b32 s53, s39
	s_mov_b32 s39, s37
	s_mov_b32 s37, s53
	s_branch .Lprep_cjoin_1

.Lprep_cjoin_1:
	s_lshl_b32 s41, s38, 6
	s_mul_i32 s41, s41, s40
	s_lshl_b32 s52, s37, 8
	s_add_u32 s41, s41, s52
	s_add_u32 s42, s42, s41
	s_addc_u32 s43, s43, 0
	s_lshl_b32 s52, s40, 5
	s_add_u32 s54, s42, s52
	s_addc_u32 s55, s43, 0
	v_mad_u32_u24 v5, v3, s40, v4
	s_lshl_b32 s52, s38, 8
	s_add_u32 s48, s48, s52
	s_addc_u32 s49, s49, 0
	s_lshl_b32 s52, s39, 17
	s_lshl_b32 s53, s38, 7
	s_add_u32 s52, s52, s53
	s_add_u32 s76, s50, s52
	s_addc_u32 s77, s51, 0
	global_load_dwordx4 v[28:31], v5, s[42:43] nt
	global_load_dwordx4 v[32:35], v5, s[54:55] nt
	global_load_dwordx4 v[72:75], v4, s[48:49]
	s_add_u32 s36, s34, 256
	s_cmpk_lt_u32 s36, 0x340
	s_cbranch_scc1 .Lprep_cin_2
	s_cmpk_lt_u32 s36, 0x440
	s_cbranch_scc1 .Lprep_cout_2
	s_sub_u32 s37, s36, 0x440
	s_lshr_b32 s38, s37, 3
	s_and_b32 s39, s37, 7
	s_mov_b32 s40, 0x800
	s_mov_b64 s[42:43], s[14:15]
	s_mov_b64 s[48:49], s[12:13]
	s_mov_b64 s[50:51], s[24:25]
	s_mov_b32 s88, 0
	s_branch .Lprep_cdone_2
.Lprep_cout_2:
	s_sub_u32 s37, s36, 0x340
	s_lshr_b32 s38, s37, 4
	s_and_b32 s39, s37, 15
	s_mov_b32 s40, 0x1000
	s_mov_b64 s[42:43], s[16:17]
	s_mov_b64 s[48:49], s[8:9]
	s_mov_b64 s[50:51], s[22:23]
	s_mov_b32 s88, 1
	s_branch .Lprep_cdone_2
.Lprep_cin_2:
	s_mul_i32 s38, s36, 0x4ed
	s_lshr_b32 s38, s38, 16
	s_mul_i32 s39, s38, 52
	s_sub_u32 s39, s36, s39
	s_and_b32 s41, s39, -2
	s_add_u32 s37, s39, 6
	s_cmp_eq_u32 s41, 2
	s_cselect_b32 s37, s37, s39
	s_sub_u32 s52, s39, 6
	s_cmp_eq_u32 s41, 8
	s_cselect_b32 s37, s52, s37
	s_mov_b32 s40, 0x3400
	s_mov_b64 s[42:43], s[10:11]
	s_mov_b64 s[48:49], s[8:9]
	s_mov_b64 s[50:51], s[20:21]
	s_mov_b32 s88, 0
	s_mov_b32 s53, s39
	s_mov_b32 s39, s37
	s_mov_b32 s37, s53
	s_branch .Lprep_cjoin_2

.Lprep_cjoin_2:
	s_lshl_b32 s41, s38, 6
	s_mul_i32 s41, s41, s40
	s_lshl_b32 s52, s37, 8
	s_add_u32 s41, s41, s52
	s_add_u32 s42, s42, s41
	s_addc_u32 s43, s43, 0
	s_lshl_b32 s52, s40, 5
	s_add_u32 s54, s42, s52
	s_addc_u32 s55, s43, 0
	v_mad_u32_u24 v5, v3, s40, v4
	s_lshl_b32 s52, s38, 8
	s_add_u32 s48, s48, s52
	s_addc_u32 s49, s49, 0
	s_lshl_b32 s52, s39, 17
	s_lshl_b32 s53, s38, 7
	s_add_u32 s52, s52, s53
	s_add_u32 s78, s50, s52
	s_addc_u32 s79, s51, 0
	global_load_dwordx4 v[36:39], v5, s[42:43] nt
	global_load_dwordx4 v[40:43], v5, s[54:55] nt
	global_load_dwordx4 v[76:79], v4, s[48:49]
	s_add_u32 s36, s34, 384
	s_cmpk_lt_u32 s36, 0x340
	s_cbranch_scc1 .Lprep_cin_3
	s_cmpk_lt_u32 s36, 0x440
	s_cbranch_scc1 .Lprep_cout_3
	s_sub_u32 s37, s36, 0x440
	s_lshr_b32 s38, s37, 3
	s_and_b32 s39, s37, 7
	s_mov_b32 s40, 0x800
	s_mov_b64 s[42:43], s[14:15]
	s_mov_b64 s[48:49], s[12:13]
	s_mov_b64 s[50:51], s[24:25]
	s_mov_b32 s89, 0
	s_branch .Lprep_cdone_3
.Lprep_cout_3:
	s_sub_u32 s37, s36, 0x340
	s_lshr_b32 s38, s37, 4
	s_and_b32 s39, s37, 15
	s_mov_b32 s40, 0x1000
	s_mov_b64 s[42:43], s[16:17]
	s_mov_b64 s[48:49], s[8:9]
	s_mov_b64 s[50:51], s[22:23]
	s_mov_b32 s89, 1
	s_branch .Lprep_cdone_3
.Lprep_cin_3:
	s_mul_i32 s38, s36, 0x4ed
	s_lshr_b32 s38, s38, 16
	s_mul_i32 s39, s38, 52
	s_sub_u32 s39, s36, s39
	s_and_b32 s41, s39, -2
	s_add_u32 s37, s39, 6
	s_cmp_eq_u32 s41, 2
	s_cselect_b32 s37, s37, s39
	s_sub_u32 s52, s39, 6
	s_cmp_eq_u32 s41, 8
	s_cselect_b32 s37, s52, s37
	s_mov_b32 s40, 0x3400
	s_mov_b64 s[42:43], s[10:11]
	s_mov_b64 s[48:49], s[8:9]
	s_mov_b64 s[50:51], s[20:21]
	s_mov_b32 s89, 0
	s_mov_b32 s53, s39
	s_mov_b32 s39, s37
	s_mov_b32 s37, s53
	s_branch .Lprep_cjoin_3

.Lprep_cjoin_3:
	s_lshl_b32 s41, s38, 6
	s_mul_i32 s41, s41, s40
	s_lshl_b32 s52, s37, 8
	s_add_u32 s41, s41, s52
	s_add_u32 s42, s42, s41
	s_addc_u32 s43, s43, 0
	s_lshl_b32 s52, s40, 5
	s_add_u32 s54, s42, s52
	s_addc_u32 s55, s43, 0
	v_mad_u32_u24 v5, v3, s40, v4
	s_lshl_b32 s52, s38, 8
	s_add_u32 s48, s48, s52
	s_addc_u32 s49, s49, 0
	s_lshl_b32 s52, s39, 17
	s_lshl_b32 s53, s38, 7
	s_add_u32 s52, s52, s53
	s_add_u32 s80, s50, s52
	s_addc_u32 s81, s51, 0
	global_load_dwordx4 v[44:47], v5, s[42:43] nt
	global_load_dwordx4 v[48:51], v5, s[54:55] nt
	global_load_dwordx4 v[80:83], v4, s[48:49]
	s_cmp_lt_u32 4, s92
	s_cbranch_scc0 .Lprep_ld_rows
	s_add_u32 s36, s34, 512
	s_cmpk_lt_u32 s36, 0x340
	s_cbranch_scc1 .Lprep_cin_4
	s_cmpk_lt_u32 s36, 0x440
	s_cbranch_scc1 .Lprep_cout_4
	s_sub_u32 s37, s36, 0x440
	s_lshr_b32 s38, s37, 3
	s_and_b32 s39, s37, 7
	s_mov_b32 s40, 0x800
	s_mov_b64 s[42:43], s[14:15]
	s_mov_b64 s[48:49], s[12:13]
	s_mov_b64 s[50:51], s[24:25]
	s_mov_b32 s90, 0
	s_branch .Lprep_cdone_4
.Lprep_cout_4:
	s_sub_u32 s37, s36, 0x340
	s_lshr_b32 s38, s37, 4
	s_and_b32 s39, s37, 15
	s_mov_b32 s40, 0x1000
	s_mov_b64 s[42:43], s[16:17]
	s_mov_b64 s[48:49], s[8:9]
	s_mov_b64 s[50:51], s[22:23]
	s_mov_b32 s90, 1
	s_branch .Lprep_cdone_4
.Lprep_cin_4:
	s_mul_i32 s38, s36, 0x4ed
	s_lshr_b32 s38, s38, 16
	s_mul_i32 s39, s38, 52
	s_sub_u32 s39, s36, s39
	s_and_b32 s41, s39, -2
	s_add_u32 s37, s39, 6
	s_cmp_eq_u32 s41, 2
	s_cselect_b32 s37, s37, s39
	s_sub_u32 s52, s39, 6
	s_cmp_eq_u32 s41, 8
	s_cselect_b32 s37, s52, s37
	s_mov_b32 s40, 0x3400
	s_mov_b64 s[42:43], s[10:11]
	s_mov_b64 s[48:49], s[8:9]
	s_mov_b64 s[50:51], s[20:21]
	s_mov_b32 s90, 0
	s_mov_b32 s53, s39
	s_mov_b32 s39, s37
	s_mov_b32 s37, s53
	s_branch .Lprep_cjoin_4

.Lprep_cjoin_4:
	s_lshl_b32 s41, s38, 6
	s_mul_i32 s41, s41, s40
	s_lshl_b32 s52, s37, 8
	s_add_u32 s41, s41, s52
	s_add_u32 s42, s42, s41
	s_addc_u32 s43, s43, 0
	s_lshl_b32 s52, s40, 5
	s_add_u32 s54, s42, s52
	s_addc_u32 s55, s43, 0
	v_mad_u32_u24 v5, v3, s40, v4
	s_lshl_b32 s52, s38, 8
	s_add_u32 s48, s48, s52
	s_addc_u32 s49, s49, 0
	s_lshl_b32 s52, s39, 17
	s_lshl_b32 s53, s38, 7
	s_add_u32 s52, s52, s53
	s_add_u32 s82, s50, s52
	s_addc_u32 s83, s51, 0
	global_load_dwordx4 v[52:55], v5, s[42:43] nt
	global_load_dwordx4 v[56:59], v5, s[54:55] nt
	global_load_dwordx4 v[84:87], v4, s[48:49]
	s_cmp_lt_u32 5, s92
	s_cbranch_scc0 .Lprep_ld_rows
	s_add_u32 s36, s34, 640
	s_cmpk_lt_u32 s36, 0x340
	s_cbranch_scc1 .Lprep_cin_5
	s_cmpk_lt_u32 s36, 0x440
	s_cbranch_scc1 .Lprep_cout_5
	s_sub_u32 s37, s36, 0x440
	s_lshr_b32 s38, s37, 3
	s_and_b32 s39, s37, 7
	s_mov_b32 s40, 0x800
	s_mov_b64 s[42:43], s[14:15]
	s_mov_b64 s[48:49], s[12:13]
	s_mov_b64 s[50:51], s[24:25]
	s_mov_b32 s91, 0
	s_branch .Lprep_cdone_5
.Lprep_cout_5:
	s_sub_u32 s37, s36, 0x340
	s_lshr_b32 s38, s37, 4
	s_and_b32 s39, s37, 15
	s_mov_b32 s40, 0x1000
	s_mov_b64 s[42:43], s[16:17]
	s_mov_b64 s[48:49], s[8:9]
	s_mov_b64 s[50:51], s[22:23]
	s_mov_b32 s91, 1
	s_branch .Lprep_cdone_5
.Lprep_cin_5:
	s_mul_i32 s38, s36, 0x4ed
	s_lshr_b32 s38, s38, 16
	s_mul_i32 s39, s38, 52
	s_sub_u32 s39, s36, s39
	s_and_b32 s41, s39, -2
	s_add_u32 s37, s39, 6
	s_cmp_eq_u32 s41, 2
	s_cselect_b32 s37, s37, s39
	s_sub_u32 s52, s39, 6
	s_cmp_eq_u32 s41, 8
	s_cselect_b32 s37, s52, s37
	s_mov_b32 s40, 0x3400
	s_mov_b64 s[42:43], s[10:11]
	s_mov_b64 s[48:49], s[8:9]
	s_mov_b64 s[50:51], s[20:21]
	s_mov_b32 s91, 0
	s_mov_b32 s53, s39
	s_mov_b32 s39, s37
	s_mov_b32 s37, s53
	s_branch .Lprep_cjoin_5

.Lprep_cjoin_5:
	s_lshl_b32 s41, s38, 6
	s_mul_i32 s41, s41, s40
	s_lshl_b32 s52, s37, 8
	s_add_u32 s41, s41, s52
	s_add_u32 s42, s42, s41
	s_addc_u32 s43, s43, 0
	s_lshl_b32 s52, s40, 5
	s_add_u32 s54, s42, s52
	s_addc_u32 s55, s43, 0
	v_mad_u32_u24 v5, v3, s40, v4
	s_lshl_b32 s52, s38, 8
	s_add_u32 s48, s48, s52
	s_addc_u32 s49, s49, 0
	s_lshl_b32 s52, s39, 17
	s_lshl_b32 s53, s38, 7
	s_add_u32 s52, s52, s53
	s_add_u32 s84, s50, s52
	s_addc_u32 s85, s51, 0
	global_load_dwordx4 v[60:63], v5, s[42:43] nt
	global_load_dwordx4 v[64:67], v5, s[54:55] nt
	global_load_dwordx4 v[88:91], v4, s[48:49]
.Lprep_ld_rows:
	s_lshl_b32 s36, s33, 12
	s_add_u32 s36, s4, s36
	s_addc_u32 s37, s5, 0
	global_load_dwordx4 v[96:99], v6, s[36:37] nt
	global_load_dwordx4 v[100:103], v6, s[36:37] offset:1024 nt
	global_load_dwordx4 v[104:107], v6, s[36:37] offset:2048 nt
	global_load_dwordx4 v[108:111], v6, s[36:37] offset:3072 nt
	s_add_u32 s36, s36, 0x800000
	s_addc_u32 s37, s37, 0
	global_load_dwordx4 v[112:115], v6, s[36:37] nt
	global_load_dwordx4 v[116:119], v6, s[36:37] offset:1024 nt
	global_load_dwordx4 v[120:123], v6, s[36:37] offset:2048 nt
	global_load_dwordx4 v[124:127], v6, s[36:37] offset:3072 nt
	s_add_u32 s36, s36, 0x800000
	s_addc_u32 s37, s37, 0
	global_load_dwordx4 v[128:131], v6, s[36:37] nt
	global_load_dwordx4 v[132:135], v6, s[36:37] offset:1024 nt
	global_load_dwordx4 v[136:139], v6, s[36:37] offset:2048 nt
	global_load_dwordx4 v[140:143], v6, s[36:37] offset:3072 nt
	s_add_u32 s36, s36, 0x800000
	s_addc_u32 s37, s37, 0
	s_waitcnt vmcnt(12)
.Lprep_tiles:
	v_mov_b32_e32 v12, 0x104
	v_mad_u32_u24 v7, v3, v12, v4
	v_add_u32_e32 v7, 16, v7
	v_add_u32_e32 v8, 0x10400, v7
	ds_write_b32 v7, v20 offset:0
	ds_write_b32 v7, v21 offset:4
	ds_write_b32 v7, v22 offset:8
	ds_write_b32 v7, v23 offset:12
	ds_write_b32 v7, v24 offset:8320
	ds_write_b32 v7, v25 offset:8324
	ds_write_b32 v7, v26 offset:8328
	ds_write_b32 v7, v27 offset:8332
	ds_write_b32 v7, v28 offset:16640
	ds_write_b32 v7, v29 offset:16644
	ds_write_b32 v7, v30 offset:16648
	ds_write_b32 v7, v31 offset:16652
	ds_write_b32 v7, v32 offset:24960
	ds_write_b32 v7, v33 offset:24964
	ds_write_b32 v7, v34 offset:24968
	ds_write_b32 v7, v35 offset:24972
	ds_write_b32 v7, v36 offset:33280
	ds_write_b32 v7, v37 offset:33284
	ds_write_b32 v7, v38 offset:33288
	ds_write_b32 v7, v39 offset:33292
	ds_write_b32 v7, v40 offset:41600
	ds_write_b32 v7, v41 offset:41604
	ds_write_b32 v7, v42 offset:41608
	ds_write_b32 v7, v43 offset:41612
	ds_write_b32 v7, v44 offset:49920
	ds_write_b32 v7, v45 offset:49924
	ds_write_b32 v7, v46 offset:49928
	ds_write_b32 v7, v47 offset:49932
	ds_write_b32 v7, v48 offset:58240
	ds_write_b32 v7, v49 offset:58244
	ds_write_b32 v7, v50 offset:58248
	ds_write_b32 v7, v51 offset:58252
	s_cmp_lt_u32 4, s92
	s_cbranch_scc0 .Lprep_wr_done
	ds_write_b32 v8, v52 offset:0
	ds_write_b32 v8, v53 offset:4
	ds_write_b32 v8, v54 offset:8
	ds_write_b32 v8, v55 offset:12
	ds_write_b32 v8, v56 offset:8320
	ds_write_b32 v8, v57 offset:8324
	ds_write_b32 v8, v58 offset:8328
	ds_write_b32 v8, v59 offset:8332
	s_cmp_lt_u32 5, s92
	s_cbranch_scc0 .Lprep_wr_done
	ds_write_b32 v8, v60 offset:16640
	ds_write_b32 v8, v61 offset:16644
	ds_write_b32 v8, v62 offset:16648
	ds_write_b32 v8, v63 offset:16652
	ds_write_b32 v8, v64 offset:24960
	ds_write_b32 v8, v65 offset:24964
	ds_write_b32 v8, v66 offset:24968
	ds_write_b32 v8, v67 offset:24972
.Lprep_wr_done:
	s_waitcnt lgkmcnt(0)
	s_barrier
	v_and_b32_e32 v12, 15, v0
	v_mov_b32_e32 v13, 0x410
	v_lshlrev_b32_e32 v9, 2, v3
	v_mad_u32_u24 v9, v12, v13, v9
	v_add_u32_e32 v9, 16, v9
	v_lshlrev_b32_e32 v10, 11, v3
	v_lshl_add_u32 v10, v12, 3, v10
	s_cmp_eq_u32 s86, 0
	s_cbranch_scc1 .Lprep_gain_0
	v_mov_b32_e32 v68, 1.0
	v_mov_b32_e32 v69, 1.0
	v_mov_b32_e32 v70, 1.0
	v_mov_b32_e32 v71, 1.0
.Lprep_gain_0:
	ds_read2_b32 v[20:21], v9 offset0:0 offset1:65
	ds_read2_b32 v[22:23], v9 offset0:130 offset1:195
	ds_read2_b32 v[24:25], v9 offset0:32 offset1:97
	ds_read2_b32 v[26:27], v9 offset0:162 offset1:227
	s_add_u32 s58, s74, 0x10000
	s_addc_u32 s59, s75, 0
	s_waitcnt lgkmcnt(2)
	v_pk_mul_f32 v[20:21], v[20:21], v[68:69]
	v_pk_mul_f32 v[22:23], v[22:23], v[70:71]
	v_cvt_pk_bf16_f32 v20, v20, v21
	v_cvt_pk_bf16_f32 v21, v22, v23
	global_store_dwordx2 v10, v[20:21], s[74:75]
	s_waitcnt lgkmcnt(0)
	v_pk_mul_f32 v[24:25], v[24:25], v[68:69]
	v_pk_mul_f32 v[26:27], v[26:27], v[70:71]
	v_cvt_pk_bf16_f32 v24, v24, v25
	v_cvt_pk_bf16_f32 v25, v26, v27
	global_store_dwordx2 v10, v[24:25], s[58:59]
	v_add_u32_e32 v9, 0x4100, v9
	s_cmp_eq_u32 s87, 0
	s_cbranch_scc1 .Lprep_gain_1
	v_mov_b32_e32 v72, 1.0
	v_mov_b32_e32 v73, 1.0
	v_mov_b32_e32 v74, 1.0
	v_mov_b32_e32 v75, 1.0
.Lprep_gain_1:
	ds_read2_b32 v[28:29], v9 offset0:0 offset1:65
	ds_read2_b32 v[30:31], v9 offset0:130 offset1:195
	ds_read2_b32 v[32:33], v9 offset0:32 offset1:97
	ds_read2_b32 v[34:35], v9 offset0:162 offset1:227
	s_add_u32 s58, s76, 0x10000
	s_addc_u32 s59, s77, 0
	s_waitcnt lgkmcnt(2)
	v_pk_mul_f32 v[28:29], v[28:29], v[72:73]
	v_pk_mul_f32 v[30:31], v[30:31], v[74:75]
	v_cvt_pk_bf16_f32 v28, v28, v29
	v_cvt_pk_bf16_f32 v29, v30, v31
	global_store_dwordx2 v10, v[28:29], s[76:77]
	s_waitcnt lgkmcnt(0)
	v_pk_mul_f32 v[32:33], v[32:33], v[72:73]
	v_pk_mul_f32 v[34:35], v[34:35], v[74:75]
	v_cvt_pk_bf16_f32 v32, v32, v33
	v_cvt_pk_bf16_f32 v33, v34, v35
	global_store_dwordx2 v10, v[32:33], s[58:59]
	v_add_u32_e32 v9, 0x4100, v9
	s_cmp_eq_u32 s88, 0
	s_cbranch_scc1 .Lprep_gain_2
	v_mov_b32_e32 v76, 1.0
	v_mov_b32_e32 v77, 1.0
	v_mov_b32_e32 v78, 1.0
	v_mov_b32_e32 v79, 1.0
.Lprep_gain_2:
	ds_read2_b32 v[36:37], v9 offset0:0 offset1:65
	ds_read2_b32 v[38:39], v9 offset0:130 offset1:195
	ds_read2_b32 v[40:41], v9 offset0:32 offset1:97
	ds_read2_b32 v[42:43], v9 offset0:162 offset1:227
	s_add_u32 s58, s78, 0x10000
	s_addc_u32 s59, s79, 0
	s_waitcnt lgkmcnt(2)
	v_pk_mul_f32 v[36:37], v[36:37], v[76:77]
	v_pk_mul_f32 v[38:39], v[38:39], v[78:79]
	v_cvt_pk_bf16_f32 v36, v36, v37
	v_cvt_pk_bf16_f32 v37, v38, v39
	global_store_dwordx2 v10, v[36:37], s[78:79]
	s_waitcnt lgkmcnt(0)
	v_pk_mul_f32 v[40:41], v[40:41], v[76:77]
	v_pk_mul_f32 v[42:43], v[42:43], v[78:79]
	v_cvt_pk_bf16_f32 v40, v40, v41
	v_cvt_pk_bf16_f32 v41, v42, v43
	global_store_dwordx2 v10, v[40:41], s[58:59]
	v_add_u32_e32 v9, 0x4100, v9
	s_cmp_eq_u32 s89, 0
	s_cbranch_scc1 .Lprep_gain_3
	v_mov_b32_e32 v80, 1.0
	v_mov_b32_e32 v81, 1.0
	v_mov_b32_e32 v82, 1.0
	v_mov_b32_e32 v83, 1.0
.Lprep_gain_3:
	ds_read2_b32 v[44:45], v9 offset0:0 offset1:65
	ds_read2_b32 v[46:47], v9 offset0:130 offset1:195
	ds_read2_b32 v[48:49], v9 offset0:32 offset1:97
	ds_read2_b32 v[50:51], v9 offset0:162 offset1:227
	s_add_u32 s58, s80, 0x10000
	s_addc_u32 s59, s81, 0
	s_waitcnt lgkmcnt(2)
	v_pk_mul_f32 v[44:45], v[44:45], v[80:81]
	v_pk_mul_f32 v[46:47], v[46:47], v[82:83]
	v_cvt_pk_bf16_f32 v44, v44, v45
	v_cvt_pk_bf16_f32 v45, v46, v47
	global_store_dwordx2 v10, v[44:45], s[80:81]
	s_waitcnt lgkmcnt(0)
	v_pk_mul_f32 v[48:49], v[48:49], v[80:81]
	v_pk_mul_f32 v[50:51], v[50:51], v[82:83]
	v_cvt_pk_bf16_f32 v48, v48, v49
	v_cvt_pk_bf16_f32 v49, v50, v51
	global_store_dwordx2 v10, v[48:49], s[58:59]
	v_add_u32_e32 v9, 0x4100, v9
	s_cmp_lt_u32 4, s92
	s_cbranch_scc0 .Lprep_rows
	s_cmp_eq_u32 s90, 0
	s_cbranch_scc1 .Lprep_gain_4
	v_mov_b32_e32 v84, 1.0
	v_mov_b32_e32 v85, 1.0
	v_mov_b32_e32 v86, 1.0
	v_mov_b32_e32 v87, 1.0
.Lprep_gain_4:
	ds_read2_b32 v[52:53], v9 offset0:0 offset1:65
	ds_read2_b32 v[54:55], v9 offset0:130 offset1:195
	ds_read2_b32 v[56:57], v9 offset0:32 offset1:97
	ds_read2_b32 v[58:59], v9 offset0:162 offset1:227
	s_add_u32 s58, s82, 0x10000
	s_addc_u32 s59, s83, 0
	s_waitcnt lgkmcnt(2)
	v_pk_mul_f32 v[52:53], v[52:53], v[84:85]
	v_pk_mul_f32 v[54:55], v[54:55], v[86:87]
	v_cvt_pk_bf16_f32 v52, v52, v53
	v_cvt_pk_bf16_f32 v53, v54, v55
	global_store_dwordx2 v10, v[52:53], s[82:83]
	s_waitcnt lgkmcnt(0)
	v_pk_mul_f32 v[56:57], v[56:57], v[84:85]
	v_pk_mul_f32 v[58:59], v[58:59], v[86:87]
	v_cvt_pk_bf16_f32 v56, v56, v57
	v_cvt_pk_bf16_f32 v57, v58, v59
	global_store_dwordx2 v10, v[56:57], s[58:59]
	v_add_u32_e32 v9, 0x4100, v9
	s_cmp_lt_u32 5, s92
	s_cbranch_scc0 .Lprep_rows
	s_cmp_eq_u32 s91, 0
	s_cbranch_scc1 .Lprep_gain_5
	v_mov_b32_e32 v88, 1.0
	v_mov_b32_e32 v89, 1.0
	v_mov_b32_e32 v90, 1.0
	v_mov_b32_e32 v91, 1.0
.Lprep_gain_5:
	ds_read2_b32 v[60:61], v9 offset0:0 offset1:65
	ds_read2_b32 v[62:63], v9 offset0:130 offset1:195
	ds_read2_b32 v[64:65], v9 offset0:32 offset1:97
	ds_read2_b32 v[66:67], v9 offset0:162 offset1:227
	s_add_u32 s58, s84, 0x10000
	s_addc_u32 s59, s85, 0
	s_waitcnt lgkmcnt(2)
	v_pk_mul_f32 v[60:61], v[60:61], v[88:89]
	v_pk_mul_f32 v[62:63], v[62:63], v[90:91]
	v_cvt_pk_bf16_f32 v60, v60, v61
	v_cvt_pk_bf16_f32 v61, v62, v63
	global_store_dwordx2 v10, v[60:61], s[84:85]
	s_waitcnt lgkmcnt(0)
	v_pk_mul_f32 v[64:65], v[64:65], v[88:89]
	v_pk_mul_f32 v[66:67], v[66:67], v[90:91]
	v_cvt_pk_bf16_f32 v64, v64, v65
	v_cvt_pk_bf16_f32 v65, v66, v67
	global_store_dwordx2 v10, v[64:65], s[58:59]
.Lprep_rows:
	v_mov_b32_e32 v17, 0x358637bd
	s_lshl_b32 s56, s33, 11
	s_add_u32 s56, s28, s56
	s_addc_u32 s57, s29, 0
	s_cmpk_lt_u32 s2, 0x80
	s_cbranch_scc0 .Lprep_rows8
	s_waitcnt vmcnt(16)
	v_pk_mul_f32 v[240:241], v[96:97], v[96:97]
	v_pk_mul_f32 v[242:243], v[104:105], v[104:105]
	v_pk_fma_f32 v[240:241], v[98:99], v[98:99], v[240:241]
	v_pk_fma_f32 v[242:243], v[106:107], v[106:107], v[242:243]
	v_pk_fma_f32 v[240:241], v[100:101], v[100:101], v[240:241]
	v_pk_fma_f32 v[242:243], v[108:109], v[108:109], v[242:243]
	v_pk_fma_f32 v[240:241], v[102:103], v[102:103], v[240:241]
	v_pk_fma_f32 v[242:243], v[110:111], v[110:111], v[242:243]
	v_pk_add_f32 v[240:241], v[240:241], v[242:243]
	s_nop 0
	v_add_f32_e32 v244, v240, v241
	s_nop 1
	v_add_f32_dpp v244, v244, v244 quad_perm:[1,0,3,2] row_mask:0xf bank_mask:0xf
	s_nop 1
	v_add_f32_dpp v244, v244, v244 quad_perm:[2,3,0,1] row_mask:0xf bank_mask:0xf
	s_nop 1
	v_add_f32_dpp v244, v244, v244 row_half_mirror row_mask:0xf bank_mask:0xf
	s_nop 1
	v_add_f32_dpp v244, v244, v244 row_mirror row_mask:0xf bank_mask:0xf
	s_nop 1
	v_readlane_b32 s38, v244, 0
	v_readlane_b32 s39, v244, 16
	v_readlane_b32 s40, v244, 32
	v_readlane_b32 s41, v244, 48
	s_nop 1
	v_mov_b32_e32 v246, s38
	v_add_f32_e32 v246, s39, v246
	v_add_f32_e32 v246, s40, v246
	v_add_f32_e32 v246, s41, v246
	v_fmamk_f32 v246, v246, 0x3a800000, v17
	v_rsq_f32_e32 v246, v246
	s_nop 0
	v_pk_mul_f32 v[96:97], v[96:97], v[246:247] op_sel_hi:[1,0]
	v_pk_mul_f32 v[98:99], v[98:99], v[246:247] op_sel_hi:[1,0]
	v_pk_mul_f32 v[100:101], v[100:101], v[246:247] op_sel_hi:[1,0]
	v_pk_mul_f32 v[102:103], v[102:103], v[246:247] op_sel_hi:[1,0]
	v_pk_mul_f32 v[104:105], v[104:105], v[246:247] op_sel_hi:[1,0]
	v_pk_mul_f32 v[106:107], v[106:107], v[246:247] op_sel_hi:[1,0]
	v_pk_mul_f32 v[108:109], v[108:109], v[246:247] op_sel_hi:[1,0]
	v_pk_mul_f32 v[110:111], v[110:111], v[246:247] op_sel_hi:[1,0]
	v_cvt_pk_bf16_f32 v96, v96, v97
	v_cvt_pk_bf16_f32 v97, v98, v99
	v_cvt_pk_bf16_f32 v98, v100, v101
	v_cvt_pk_bf16_f32 v99, v102, v103
	v_cvt_pk_bf16_f32 v100, v104, v105
	v_cvt_pk_bf16_f32 v101, v106, v107
	v_cvt_pk_bf16_f32 v102, v108, v109
	v_cvt_pk_bf16_f32 v103, v110, v111
	global_store_dwordx2 v11, v[96:97], s[56:57]
	global_store_dwordx2 v11, v[98:99], s[56:57] offset:512
	global_store_dwordx2 v11, v[100:101], s[56:57] offset:1024
	global_store_dwordx2 v11, v[102:103], s[56:57] offset:1536
	s_add_u32 s56, s56, 0x400000
	s_addc_u32 s57, s57, 0
	global_load_dwordx4 v[96:99], v6, s[36:37] nt
	global_load_dwordx4 v[100:103], v6, s[36:37] offset:1024 nt
	global_load_dwordx4 v[104:107], v6, s[36:37] offset:2048 nt
	global_load_dwordx4 v[108:111], v6, s[36:37] offset:3072 nt
	s_add_u32 s36, s36, 0x800000
	s_addc_u32 s37, s37, 0
	s_waitcnt vmcnt(20)
	v_pk_mul_f32 v[240:241], v[112:113], v[112:113]
	v_pk_mul_f32 v[242:243], v[120:121], v[120:121]
	v_pk_fma_f32 v[240:241], v[114:115], v[114:115], v[240:241]
	v_pk_fma_f32 v[242:243], v[122:123], v[122:123], v[242:243]
	v_pk_fma_f32 v[240:241], v[116:117], v[116:117], v[240:241]
	v_pk_fma_f32 v[242:243], v[124:125], v[124:125], v[242:243]
	v_pk_fma_f32 v[240:241], v[118:119], v[118:119], v[240:241]
	v_pk_fma_f32 v[242:243], v[126:127], v[126:127], v[242:243]
	v_pk_add_f32 v[240:241], v[240:241], v[242:243]
	s_nop 0
	v_add_f32_e32 v244, v240, v241
	s_nop 1
	v_add_f32_dpp v244, v244, v244 quad_perm:[1,0,3,2] row_mask:0xf bank_mask:0xf
	s_nop 1
	v_add_f32_dpp v244, v244, v244 quad_perm:[2,3,0,1] row_mask:0xf bank_mask:0xf
	s_nop 1
	v_add_f32_dpp v244, v244, v244 row_half_mirror row_mask:0xf bank_mask:0xf
	s_nop 1
	v_add_f32_dpp v244, v244, v244 row_mirror row_mask:0xf bank_mask:0xf
	s_nop 1
	v_readlane_b32 s38, v244, 0
	v_readlane_b32 s39, v244, 16
	v_readlane_b32 s40, v244, 32
	v_readlane_b32 s41, v244, 48
	s_nop 1
	v_mov_b32_e32 v246, s38
	v_add_f32_e32 v246, s39, v246
	v_add_f32_e32 v246, s40, v246
	v_add_f32_e32 v246, s41, v246
	v_fmamk_f32 v246, v246, 0x3a800000, v17
	v_rsq_f32_e32 v246, v246
	s_nop 0
	v_pk_mul_f32 v[112:113], v[112:113], v[246:247] op_sel_hi:[1,0]
	v_pk_mul_f32 v[114:115], v[114:115], v[246:247] op_sel_hi:[1,0]
	v_pk_mul_f32 v[116:117], v[116:117], v[246:247] op_sel_hi:[1,0]
	v_pk_mul_f32 v[118:119], v[118:119], v[246:247] op_sel_hi:[1,0]
	v_pk_mul_f32 v[120:121], v[120:121], v[246:247] op_sel_hi:[1,0]
	v_pk_mul_f32 v[122:123], v[122:123], v[246:247] op_sel_hi:[1,0]
	v_pk_mul_f32 v[124:125], v[124:125], v[246:247] op_sel_hi:[1,0]
	v_pk_mul_f32 v[126:127], v[126:127], v[246:247] op_sel_hi:[1,0]
	v_cvt_pk_bf16_f32 v112, v112, v113
	v_cvt_pk_bf16_f32 v113, v114, v115
	v_cvt_pk_bf16_f32 v114, v116, v117
	v_cvt_pk_bf16_f32 v115, v118, v119
	v_cvt_pk_bf16_f32 v116, v120, v121
	v_cvt_pk_bf16_f32 v117, v122, v123
	v_cvt_pk_bf16_f32 v118, v124, v125
	v_cvt_pk_bf16_f32 v119, v126, v127
	global_store_dwordx2 v11, v[112:113], s[56:57]
	global_store_dwordx2 v11, v[114:115], s[56:57] offset:512
	global_store_dwordx2 v11, v[116:117], s[56:57] offset:1024
	global_store_dwordx2 v11, v[118:119], s[56:57] offset:1536
	s_add_u32 s56, s56, 0x400000
	s_addc_u32 s57, s57, 0
	global_load_dwordx4 v[112:115], v6, s[36:37] nt
	global_load_dwordx4 v[116:119], v6, s[36:37] offset:1024 nt
	global_load_dwordx4 v[120:123], v6, s[36:37] offset:2048 nt
	global_load_dwordx4 v[124:127], v6, s[36:37] offset:3072 nt
	s_add_u32 s36, s36, 0x800000
	s_addc_u32 s37, s37, 0
	s_waitcnt vmcnt(24)
	v_pk_mul_f32 v[240:241], v[128:129], v[128:129]
	v_pk_mul_f32 v[242:243], v[136:137], v[136:137]
	v_pk_fma_f32 v[240:241], v[130:131], v[130:131], v[240:241]
	v_pk_fma_f32 v[242:243], v[138:139], v[138:139], v[242:243]
	v_pk_fma_f32 v[240:241], v[132:133], v[132:133], v[240:241]
	v_pk_fma_f32 v[242:243], v[140:141], v[140:141], v[242:243]
	v_pk_fma_f32 v[240:241], v[134:135], v[134:135], v[240:241]
	v_pk_fma_f32 v[242:243], v[142:143], v[142:143], v[242:243]
	v_pk_add_f32 v[240:241], v[240:241], v[242:243]
	s_nop 0
	v_add_f32_e32 v244, v240, v241
	s_nop 1
	v_add_f32_dpp v244, v244, v244 quad_perm:[1,0,3,2] row_mask:0xf bank_mask:0xf
	s_nop 1
	v_add_f32_dpp v244, v244, v244 quad_perm:[2,3,0,1] row_mask:0xf bank_mask:0xf
	s_nop 1
	v_add_f32_dpp v244, v244, v244 row_half_mirror row_mask:0xf bank_mask:0xf
	s_nop 1
	v_add_f32_dpp v244, v244, v244 row_mirror row_mask:0xf bank_mask:0xf
	s_nop 1
	v_readlane_b32 s38, v244, 0
	v_readlane_b32 s39, v244, 16
	v_readlane_b32 s40, v244, 32
	v_readlane_b32 s41, v244, 48
	s_nop 1
	v_mov_b32_e32 v246, s38
	v_add_f32_e32 v246, s39, v246
	v_add_f32_e32 v246, s40, v246
	v_add_f32_e32 v246, s41, v246
	v_fmamk_f32 v246, v246, 0x3a800000, v17
	v_rsq_f32_e32 v246, v246
	s_nop 0
	v_pk_mul_f32 v[128:129], v[128:129], v[246:247] op_sel_hi:[1,0]
	v_pk_mul_f32 v[130:131], v[130:131], v[246:247] op_sel_hi:[1,0]
	v_pk_mul_f32 v[132:133], v[132:133], v[246:247] op_sel_hi:[1,0]
	v_pk_mul_f32 v[134:135], v[134:135], v[246:247] op_sel_hi:[1,0]
	v_pk_mul_f32 v[136:137], v[136:137], v[246:247] op_sel_hi:[1,0]
	v_pk_mul_f32 v[138:139], v[138:139], v[246:247] op_sel_hi:[1,0]
	v_pk_mul_f32 v[140:141], v[140:141], v[246:247] op_sel_hi:[1,0]
	v_pk_mul_f32 v[142:143], v[142:143], v[246:247] op_sel_hi:[1,0]
	v_cvt_pk_bf16_f32 v128, v128, v129
	v_cvt_pk_bf16_f32 v129, v130, v131
	v_cvt_pk_bf16_f32 v130, v132, v133
	v_cvt_pk_bf16_f32 v131, v134, v135
	v_cvt_pk_bf16_f32 v132, v136, v137
	v_cvt_pk_bf16_f32 v133, v138, v139
	v_cvt_pk_bf16_f32 v134, v140, v141
	v_cvt_pk_bf16_f32 v135, v142, v143
	global_store_dwordx2 v11, v[128:129], s[56:57]
	global_store_dwordx2 v11, v[130:131], s[56:57] offset:512
	global_store_dwordx2 v11, v[132:133], s[56:57] offset:1024
	global_store_dwordx2 v11, v[134:135], s[56:57] offset:1536
	s_add_u32 s56, s56, 0x400000
	s_addc_u32 s57, s57, 0
	global_load_dwordx4 v[128:131], v6, s[36:37] nt
	global_load_dwordx4 v[132:135], v6, s[36:37] offset:1024 nt
	global_load_dwordx4 v[136:139], v6, s[36:37] offset:2048 nt
	global_load_dwordx4 v[140:143], v6, s[36:37] offset:3072 nt
	s_add_u32 s36, s36, 0x800000
	s_addc_u32 s37, s37, 0
	s_waitcnt vmcnt(16)
	v_pk_mul_f32 v[240:241], v[96:97], v[96:97]
	v_pk_mul_f32 v[242:243], v[104:105], v[104:105]
	v_pk_fma_f32 v[240:241], v[98:99], v[98:99], v[240:241]
	v_pk_fma_f32 v[242:243], v[106:107], v[106:107], v[242:243]
	v_pk_fma_f32 v[240:241], v[100:101], v[100:101], v[240:241]
	v_pk_fma_f32 v[242:243], v[108:109], v[108:109], v[242:243]
	v_pk_fma_f32 v[240:241], v[102:103], v[102:103], v[240:241]
	v_pk_fma_f32 v[242:243], v[110:111], v[110:111], v[242:243]
	v_pk_add_f32 v[240:241], v[240:241], v[242:243]
	s_nop 0
	v_add_f32_e32 v244, v240, v241
	s_nop 1
	v_add_f32_dpp v244, v244, v244 quad_perm:[1,0,3,2] row_mask:0xf bank_mask:0xf
	s_nop 1
	v_add_f32_dpp v244, v244, v244 quad_perm:[2,3,0,1] row_mask:0xf bank_mask:0xf
	s_nop 1
	v_add_f32_dpp v244, v244, v244 row_half_mirror row_mask:0xf bank_mask:0xf
	s_nop 1
	v_add_f32_dpp v244, v244, v244 row_mirror row_mask:0xf bank_mask:0xf
	s_nop 1
	v_readlane_b32 s38, v244, 0
	v_readlane_b32 s39, v244, 16
	v_readlane_b32 s40, v244, 32
	v_readlane_b32 s41, v244, 48
	s_nop 1
	v_mov_b32_e32 v246, s38
	v_add_f32_e32 v246, s39, v246
	v_add_f32_e32 v246, s40, v246
	v_add_f32_e32 v246, s41, v246
	v_fmamk_f32 v246, v246, 0x3a800000, v17
	v_rsq_f32_e32 v246, v246
	s_nop 0
	v_pk_mul_f32 v[96:97], v[96:97], v[246:247] op_sel_hi:[1,0]
	v_pk_mul_f32 v[98:99], v[98:99], v[246:247] op_sel_hi:[1,0]
	v_pk_mul_f32 v[100:101], v[100:101], v[246:247] op_sel_hi:[1,0]
	v_pk_mul_f32 v[102:103], v[102:103], v[246:247] op_sel_hi:[1,0]
	v_pk_mul_f32 v[104:105], v[104:105], v[246:247] op_sel_hi:[1,0]
	v_pk_mul_f32 v[106:107], v[106:107], v[246:247] op_sel_hi:[1,0]
	v_pk_mul_f32 v[108:109], v[108:109], v[246:247] op_sel_hi:[1,0]
	v_pk_mul_f32 v[110:111], v[110:111], v[246:247] op_sel_hi:[1,0]
	v_cvt_pk_bf16_f32 v96, v96, v97
	v_cvt_pk_bf16_f32 v97, v98, v99
	v_cvt_pk_bf16_f32 v98, v100, v101
	v_cvt_pk_bf16_f32 v99, v102, v103
	v_cvt_pk_bf16_f32 v100, v104, v105
	v_cvt_pk_bf16_f32 v101, v106, v107
	v_cvt_pk_bf16_f32 v102, v108, v109
	v_cvt_pk_bf16_f32 v103, v110, v111
	global_store_dwordx2 v11, v[96:97], s[56:57]
	global_store_dwordx2 v11, v[98:99], s[56:57] offset:512
	global_store_dwordx2 v11, v[100:101], s[56:57] offset:1024
	global_store_dwordx2 v11, v[102:103], s[56:57] offset:1536
	s_add_u32 s56, s56, 0x400000
	s_addc_u32 s57, s57, 0
	global_load_dwordx4 v[96:99], v6, s[36:37] nt
	global_load_dwordx4 v[100:103], v6, s[36:37] offset:1024 nt
	global_load_dwordx4 v[104:107], v6, s[36:37] offset:2048 nt
	global_load_dwordx4 v[108:111], v6, s[36:37] offset:3072 nt
	s_add_u32 s36, s36, 0x800000
	s_addc_u32 s37, s37, 0
	s_waitcnt vmcnt(16)
	v_pk_mul_f32 v[240:241], v[112:113], v[112:113]
	v_pk_mul_f32 v[242:243], v[120:121], v[120:121]
	v_pk_fma_f32 v[240:241], v[114:115], v[114:115], v[240:241]
	v_pk_fma_f32 v[242:243], v[122:123], v[122:123], v[242:243]
	v_pk_fma_f32 v[240:241], v[116:117], v[116:117], v[240:241]
	v_pk_fma_f32 v[242:243], v[124:125], v[124:125], v[242:243]
	v_pk_fma_f32 v[240:241], v[118:119], v[118:119], v[240:241]
	v_pk_fma_f32 v[242:243], v[126:127], v[126:127], v[242:243]
	v_pk_add_f32 v[240:241], v[240:241], v[242:243]
	s_nop 0
	v_add_f32_e32 v244, v240, v241
	s_nop 1
	v_add_f32_dpp v244, v244, v244 quad_perm:[1,0,3,2] row_mask:0xf bank_mask:0xf
	s_nop 1
	v_add_f32_dpp v244, v244, v244 quad_perm:[2,3,0,1] row_mask:0xf bank_mask:0xf
	s_nop 1
	v_add_f32_dpp v244, v244, v244 row_half_mirror row_mask:0xf bank_mask:0xf
	s_nop 1
	v_add_f32_dpp v244, v244, v244 row_mirror row_mask:0xf bank_mask:0xf
	s_nop 1
	v_readlane_b32 s38, v244, 0
	v_readlane_b32 s39, v244, 16
	v_readlane_b32 s40, v244, 32
	v_readlane_b32 s41, v244, 48
	s_nop 1
	v_mov_b32_e32 v246, s38
	v_add_f32_e32 v246, s39, v246
	v_add_f32_e32 v246, s40, v246
	v_add_f32_e32 v246, s41, v246
	v_fmamk_f32 v246, v246, 0x3a800000, v17
	v_rsq_f32_e32 v246, v246
	s_nop 0
	v_pk_mul_f32 v[112:113], v[112:113], v[246:247] op_sel_hi:[1,0]
	v_pk_mul_f32 v[114:115], v[114:115], v[246:247] op_sel_hi:[1,0]
	v_pk_mul_f32 v[116:117], v[116:117], v[246:247] op_sel_hi:[1,0]
	v_pk_mul_f32 v[118:119], v[118:119], v[246:247] op_sel_hi:[1,0]
	v_pk_mul_f32 v[120:121], v[120:121], v[246:247] op_sel_hi:[1,0]
	v_pk_mul_f32 v[122:123], v[122:123], v[246:247] op_sel_hi:[1,0]
	v_pk_mul_f32 v[124:125], v[124:125], v[246:247] op_sel_hi:[1,0]
	v_pk_mul_f32 v[126:127], v[126:127], v[246:247] op_sel_hi:[1,0]
	v_cvt_pk_bf16_f32 v112, v112, v113
	v_cvt_pk_bf16_f32 v113, v114, v115
	v_cvt_pk_bf16_f32 v114, v116, v117
	v_cvt_pk_bf16_f32 v115, v118, v119
	v_cvt_pk_bf16_f32 v116, v120, v121
	v_cvt_pk_bf16_f32 v117, v122, v123
	v_cvt_pk_bf16_f32 v118, v124, v125
	v_cvt_pk_bf16_f32 v119, v126, v127
	global_store_dwordx2 v11, v[112:113], s[56:57]
	global_store_dwordx2 v11, v[114:115], s[56:57] offset:512
	global_store_dwordx2 v11, v[116:117], s[56:57] offset:1024
	global_store_dwordx2 v11, v[118:119], s[56:57] offset:1536
	s_add_u32 s56, s56, 0x400000
	s_addc_u32 s57, s57, 0
	global_load_dwordx4 v[112:115], v6, s[36:37] nt
	global_load_dwordx4 v[116:119], v6, s[36:37] offset:1024 nt
	global_load_dwordx4 v[120:123], v6, s[36:37] offset:2048 nt
	global_load_dwordx4 v[124:127], v6, s[36:37] offset:3072 nt
	s_waitcnt vmcnt(16)
	v_pk_mul_f32 v[240:241], v[128:129], v[128:129]
	v_pk_mul_f32 v[242:243], v[136:137], v[136:137]
	v_pk_fma_f32 v[240:241], v[130:131], v[130:131], v[240:241]
	v_pk_fma_f32 v[242:243], v[138:139], v[138:139], v[242:243]
	v_pk_fma_f32 v[240:241], v[132:133], v[132:133], v[240:241]
	v_pk_fma_f32 v[242:243], v[140:141], v[140:141], v[242:243]
	v_pk_fma_f32 v[240:241], v[134:135], v[134:135], v[240:241]
	v_pk_fma_f32 v[242:243], v[142:143], v[142:143], v[242:243]
	v_pk_add_f32 v[240:241], v[240:241], v[242:243]
	s_nop 0
	v_add_f32_e32 v244, v240, v241
	s_nop 1
	v_add_f32_dpp v244, v244, v244 quad_perm:[1,0,3,2] row_mask:0xf bank_mask:0xf
	s_nop 1
	v_add_f32_dpp v244, v244, v244 quad_perm:[2,3,0,1] row_mask:0xf bank_mask:0xf
	s_nop 1
	v_add_f32_dpp v244, v244, v244 row_half_mirror row_mask:0xf bank_mask:0xf
	s_nop 1
	v_add_f32_dpp v244, v244, v244 row_mirror row_mask:0xf bank_mask:0xf
	s_nop 1
	v_readlane_b32 s38, v244, 0
	v_readlane_b32 s39, v244, 16
	v_readlane_b32 s40, v244, 32
	v_readlane_b32 s41, v244, 48
	s_nop 1
	v_mov_b32_e32 v246, s38
	v_add_f32_e32 v246, s39, v246
	v_add_f32_e32 v246, s40, v246
	v_add_f32_e32 v246, s41, v246
	v_fmamk_f32 v246, v246, 0x3a800000, v17
	v_rsq_f32_e32 v246, v246
	s_nop 0
	v_pk_mul_f32 v[128:129], v[128:129], v[246:247] op_sel_hi:[1,0]
	v_pk_mul_f32 v[130:131], v[130:131], v[246:247] op_sel_hi:[1,0]
	v_pk_mul_f32 v[132:133], v[132:133], v[246:247] op_sel_hi:[1,0]
	v_pk_mul_f32 v[134:135], v[134:135], v[246:247] op_sel_hi:[1,0]
	v_pk_mul_f32 v[136:137], v[136:137], v[246:247] op_sel_hi:[1,0]
	v_pk_mul_f32 v[138:139], v[138:139], v[246:247] op_sel_hi:[1,0]
	v_pk_mul_f32 v[140:141], v[140:141], v[246:247] op_sel_hi:[1,0]
	v_pk_mul_f32 v[142:143], v[142:143], v[246:247] op_sel_hi:[1,0]
	v_cvt_pk_bf16_f32 v128, v128, v129
	v_cvt_pk_bf16_f32 v129, v130, v131
	v_cvt_pk_bf16_f32 v130, v132, v133
	v_cvt_pk_bf16_f32 v131, v134, v135
	v_cvt_pk_bf16_f32 v132, v136, v137
	v_cvt_pk_bf16_f32 v133, v138, v139
	v_cvt_pk_bf16_f32 v134, v140, v141
	v_cvt_pk_bf16_f32 v135, v142, v143
	global_store_dwordx2 v11, v[128:129], s[56:57]
	global_store_dwordx2 v11, v[130:131], s[56:57] offset:512
	global_store_dwordx2 v11, v[132:133], s[56:57] offset:1024
	global_store_dwordx2 v11, v[134:135], s[56:57] offset:1536
	s_add_u32 s56, s56, 0x400000
	s_addc_u32 s57, s57, 0
	s_lshl_b32 s36, s33, 12
	s_add_u32 s36, s6, s36
	s_addc_u32 s37, s7, 0
	global_load_dwordx4 v[128:131], v6, s[36:37] nt
	global_load_dwordx4 v[132:135], v6, s[36:37] offset:1024 nt
	global_load_dwordx4 v[136:139], v6, s[36:37] offset:2048 nt
	global_load_dwordx4 v[140:143], v6, s[36:37] offset:3072 nt
	s_waitcnt vmcnt(16)
	v_pk_mul_f32 v[240:241], v[96:97], v[96:97]
	v_pk_mul_f32 v[242:243], v[104:105], v[104:105]
	v_pk_fma_f32 v[240:241], v[98:99], v[98:99], v[240:241]
	v_pk_fma_f32 v[242:243], v[106:107], v[106:107], v[242:243]
	v_pk_fma_f32 v[240:241], v[100:101], v[100:101], v[240:241]
	v_pk_fma_f32 v[242:243], v[108:109], v[108:109], v[242:243]
	v_pk_fma_f32 v[240:241], v[102:103], v[102:103], v[240:241]
	v_pk_fma_f32 v[242:243], v[110:111], v[110:111], v[242:243]
	v_pk_add_f32 v[240:241], v[240:241], v[242:243]
	s_nop 0
	v_add_f32_e32 v244, v240, v241
	s_nop 1
	v_add_f32_dpp v244, v244, v244 quad_perm:[1,0,3,2] row_mask:0xf bank_mask:0xf
	s_nop 1
	v_add_f32_dpp v244, v244, v244 quad_perm:[2,3,0,1] row_mask:0xf bank_mask:0xf
	s_nop 1
	v_add_f32_dpp v244, v244, v244 row_half_mirror row_mask:0xf bank_mask:0xf
	s_nop 1
	v_add_f32_dpp v244, v244, v244 row_mirror row_mask:0xf bank_mask:0xf
	s_nop 1
	v_readlane_b32 s38, v244, 0
	v_readlane_b32 s39, v244, 16
	v_readlane_b32 s40, v244, 32
	v_readlane_b32 s41, v244, 48
	s_nop 1
	v_mov_b32_e32 v246, s38
	v_add_f32_e32 v246, s39, v246
	v_add_f32_e32 v246, s40, v246
	v_add_f32_e32 v246, s41, v246
	v_fmamk_f32 v246, v246, 0x3a800000, v17
	v_rsq_f32_e32 v246, v246
	s_nop 0
	v_pk_mul_f32 v[96:97], v[96:97], v[246:247] op_sel_hi:[1,0]
	v_pk_mul_f32 v[98:99], v[98:99], v[246:247] op_sel_hi:[1,0]
	v_pk_mul_f32 v[100:101], v[100:101], v[246:247] op_sel_hi:[1,0]
	v_pk_mul_f32 v[102:103], v[102:103], v[246:247] op_sel_hi:[1,0]
	v_pk_mul_f32 v[104:105], v[104:105], v[246:247] op_sel_hi:[1,0]
	v_pk_mul_f32 v[106:107], v[106:107], v[246:247] op_sel_hi:[1,0]
	v_pk_mul_f32 v[108:109], v[108:109], v[246:247] op_sel_hi:[1,0]
	v_pk_mul_f32 v[110:111], v[110:111], v[246:247] op_sel_hi:[1,0]
	v_cvt_pk_bf16_f32 v96, v96, v97
	v_cvt_pk_bf16_f32 v97, v98, v99
	v_cvt_pk_bf16_f32 v98, v100, v101
	v_cvt_pk_bf16_f32 v99, v102, v103
	v_cvt_pk_bf16_f32 v100, v104, v105
	v_cvt_pk_bf16_f32 v101, v106, v107
	v_cvt_pk_bf16_f32 v102, v108, v109
	v_cvt_pk_bf16_f32 v103, v110, v111
	global_store_dwordx2 v11, v[96:97], s[56:57]
	global_store_dwordx2 v11, v[98:99], s[56:57] offset:512
	global_store_dwordx2 v11, v[100:101], s[56:57] offset:1024
	global_store_dwordx2 v11, v[102:103], s[56:57] offset:1536
	s_add_u32 s56, s56, 0x400000
	s_addc_u32 s57, s57, 0
	s_waitcnt vmcnt(12)
	v_pk_mul_f32 v[240:241], v[112:113], v[112:113]
	v_pk_mul_f32 v[242:243], v[120:121], v[120:121]
	v_pk_fma_f32 v[240:241], v[114:115], v[114:115], v[240:241]
	v_pk_fma_f32 v[242:243], v[122:123], v[122:123], v[242:243]
	v_pk_fma_f32 v[240:241], v[116:117], v[116:117], v[240:241]
	v_pk_fma_f32 v[242:243], v[124:125], v[124:125], v[242:243]
	v_pk_fma_f32 v[240:241], v[118:119], v[118:119], v[240:241]
	v_pk_fma_f32 v[242:243], v[126:127], v[126:127], v[242:243]
	v_pk_add_f32 v[240:241], v[240:241], v[242:243]
	s_nop 0
	v_add_f32_e32 v244, v240, v241
	s_nop 1
	v_add_f32_dpp v244, v244, v244 quad_perm:[1,0,3,2] row_mask:0xf bank_mask:0xf
	s_nop 1
	v_add_f32_dpp v244, v244, v244 quad_perm:[2,3,0,1] row_mask:0xf bank_mask:0xf
	s_nop 1
	v_add_f32_dpp v244, v244, v244 row_half_mirror row_mask:0xf bank_mask:0xf
	s_nop 1
	v_add_f32_dpp v244, v244, v244 row_mirror row_mask:0xf bank_mask:0xf
	s_nop 1
	v_readlane_b32 s38, v244, 0
	v_readlane_b32 s39, v244, 16
	v_readlane_b32 s40, v244, 32
	v_readlane_b32 s41, v244, 48
	s_nop 1
	v_mov_b32_e32 v246, s38
	v_add_f32_e32 v246, s39, v246
	v_add_f32_e32 v246, s40, v246
	v_add_f32_e32 v246, s41, v246
	v_fmamk_f32 v246, v246, 0x3a800000, v17
	v_rsq_f32_e32 v246, v246
	s_nop 0
	v_pk_mul_f32 v[112:113], v[112:113], v[246:247] op_sel_hi:[1,0]
	v_pk_mul_f32 v[114:115], v[114:115], v[246:247] op_sel_hi:[1,0]
	v_pk_mul_f32 v[116:117], v[116:117], v[246:247] op_sel_hi:[1,0]
	v_pk_mul_f32 v[118:119], v[118:119], v[246:247] op_sel_hi:[1,0]
	v_pk_mul_f32 v[120:121], v[120:121], v[246:247] op_sel_hi:[1,0]
	v_pk_mul_f32 v[122:123], v[122:123], v[246:247] op_sel_hi:[1,0]
	v_pk_mul_f32 v[124:125], v[124:125], v[246:247] op_sel_hi:[1,0]
	v_pk_mul_f32 v[126:127], v[126:127], v[246:247] op_sel_hi:[1,0]
	v_cvt_pk_bf16_f32 v112, v112, v113
	v_cvt_pk_bf16_f32 v113, v114, v115
	v_cvt_pk_bf16_f32 v114, v116, v117
	v_cvt_pk_bf16_f32 v115, v118, v119
	v_cvt_pk_bf16_f32 v116, v120, v121
	v_cvt_pk_bf16_f32 v117, v122, v123
	v_cvt_pk_bf16_f32 v118, v124, v125
	v_cvt_pk_bf16_f32 v119, v126, v127
	global_store_dwordx2 v11, v[112:113], s[56:57]
	global_store_dwordx2 v11, v[114:115], s[56:57] offset:512
	global_store_dwordx2 v11, v[116:117], s[56:57] offset:1024
	global_store_dwordx2 v11, v[118:119], s[56:57] offset:1536
	s_waitcnt vmcnt(8)
	s_lshl_b32 s56, s33, 11
	s_add_u32 s56, s30, s56
	s_addc_u32 s57, s31, 0
	v_pk_mul_f32 v[240:241], v[128:129], v[128:129]
	v_pk_mul_f32 v[242:243], v[136:137], v[136:137]
	v_pk_fma_f32 v[240:241], v[130:131], v[130:131], v[240:241]
	v_pk_fma_f32 v[242:243], v[138:139], v[138:139], v[242:243]
	v_pk_fma_f32 v[240:241], v[132:133], v[132:133], v[240:241]
	v_pk_fma_f32 v[242:243], v[140:141], v[140:141], v[242:243]
	v_pk_fma_f32 v[240:241], v[134:135], v[134:135], v[240:241]
	v_pk_fma_f32 v[242:243], v[142:143], v[142:143], v[242:243]
	v_pk_add_f32 v[240:241], v[240:241], v[242:243]
	s_nop 0
	v_add_f32_e32 v244, v240, v241
	s_nop 1
	v_add_f32_dpp v244, v244, v244 quad_perm:[1,0,3,2] row_mask:0xf bank_mask:0xf
	s_nop 1
	v_add_f32_dpp v244, v244, v244 quad_perm:[2,3,0,1] row_mask:0xf bank_mask:0xf
	s_nop 1
	v_add_f32_dpp v244, v244, v244 row_half_mirror row_mask:0xf bank_mask:0xf
	s_nop 1
	v_add_f32_dpp v244, v244, v244 row_mirror row_mask:0xf bank_mask:0xf
	s_nop 1
	v_readlane_b32 s38, v244, 0
	v_readlane_b32 s39, v244, 16
	v_readlane_b32 s40, v244, 32
	v_readlane_b32 s41, v244, 48
	s_nop 1
	v_mov_b32_e32 v246, s38
	v_add_f32_e32 v246, s39, v246
	v_add_f32_e32 v246, s40, v246
	v_add_f32_e32 v246, s41, v246
	v_fmamk_f32 v246, v246, 0x3a800000, v17
	v_rsq_f32_e32 v246, v246
	s_nop 0
	v_pk_mul_f32 v[128:129], v[128:129], v[246:247] op_sel_hi:[1,0]
	v_pk_mul_f32 v[130:131], v[130:131], v[246:247] op_sel_hi:[1,0]
	v_pk_mul_f32 v[132:133], v[132:133], v[246:247] op_sel_hi:[1,0]
	v_pk_mul_f32 v[134:135], v[134:135], v[246:247] op_sel_hi:[1,0]
	v_pk_mul_f32 v[136:137], v[136:137], v[246:247] op_sel_hi:[1,0]
	v_pk_mul_f32 v[138:139], v[138:139], v[246:247] op_sel_hi:[1,0]
	v_pk_mul_f32 v[140:141], v[140:141], v[246:247] op_sel_hi:[1,0]
	v_pk_mul_f32 v[142:143], v[142:143], v[246:247] op_sel_hi:[1,0]
	v_cvt_pk_bf16_f32 v128, v128, v129
	v_cvt_pk_bf16_f32 v129, v130, v131
	v_cvt_pk_bf16_f32 v130, v132, v133
	v_cvt_pk_bf16_f32 v131, v134, v135
	v_cvt_pk_bf16_f32 v132, v136, v137
	v_cvt_pk_bf16_f32 v133, v138, v139
	v_cvt_pk_bf16_f32 v134, v140, v141
	v_cvt_pk_bf16_f32 v135, v142, v143
	global_store_dwordx2 v11, v[128:129], s[56:57]
	global_store_dwordx2 v11, v[130:131], s[56:57] offset:512
	global_store_dwordx2 v11, v[132:133], s[56:57] offset:1024
	global_store_dwordx2 v11, v[134:135], s[56:57] offset:1536
	s_branch .Lprep_done
.Lprep_rows8:
	s_waitcnt vmcnt(18)
	v_pk_mul_f32 v[240:241], v[96:97], v[96:97]
	v_pk_mul_f32 v[242:243], v[104:105], v[104:105]
	v_pk_fma_f32 v[240:241], v[98:99], v[98:99], v[240:241]
	v_pk_fma_f32 v[242:243], v[106:107], v[106:107], v[242:243]
	v_pk_fma_f32 v[240:241], v[100:101], v[100:101], v[240:241]
	v_pk_fma_f32 v[242:243], v[108:109], v[108:109], v[242:243]
	v_pk_fma_f32 v[240:241], v[102:103], v[102:103], v[240:241]
	v_pk_fma_f32 v[242:243], v[110:111], v[110:111], v[242:243]
	v_pk_add_f32 v[240:241], v[240:241], v[242:243]
	s_nop 0
	v_add_f32_e32 v244, v240, v241
	s_nop 1
	v_add_f32_dpp v244, v244, v244 quad_perm:[1,0,3,2] row_mask:0xf bank_mask:0xf
	s_nop 1
	v_add_f32_dpp v244, v244, v244 quad_perm:[2,3,0,1] row_mask:0xf bank_mask:0xf
	s_nop 1
	v_add_f32_dpp v244, v244, v244 row_half_mirror row_mask:0xf bank_mask:0xf
	s_nop 1
	v_add_f32_dpp v244, v244, v244 row_mirror row_mask:0xf bank_mask:0xf
	s_nop 1
	v_readlane_b32 s38, v244, 0
	v_readlane_b32 s39, v244, 16
	v_readlane_b32 s40, v244, 32
	v_readlane_b32 s41, v244, 48
	s_nop 1
	v_mov_b32_e32 v246, s38
	v_add_f32_e32 v246, s39, v246
	v_add_f32_e32 v246, s40, v246
	v_add_f32_e32 v246, s41, v246
	v_fmamk_f32 v246, v246, 0x3a800000, v17
	v_rsq_f32_e32 v246, v246
	s_nop 0
	v_pk_mul_f32 v[96:97], v[96:97], v[246:247] op_sel_hi:[1,0]
	v_pk_mul_f32 v[98:99], v[98:99], v[246:247] op_sel_hi:[1,0]
	v_pk_mul_f32 v[100:101], v[100:101], v[246:247] op_sel_hi:[1,0]
	v_pk_mul_f32 v[102:103], v[102:103], v[246:247] op_sel_hi:[1,0]
	v_pk_mul_f32 v[104:105], v[104:105], v[246:247] op_sel_hi:[1,0]
	v_pk_mul_f32 v[106:107], v[106:107], v[246:247] op_sel_hi:[1,0]
	v_pk_mul_f32 v[108:109], v[108:109], v[246:247] op_sel_hi:[1,0]
	v_pk_mul_f32 v[110:111], v[110:111], v[246:247] op_sel_hi:[1,0]
	v_cvt_pk_bf16_f32 v96, v96, v97
	v_cvt_pk_bf16_f32 v97, v98, v99
	v_cvt_pk_bf16_f32 v98, v100, v101
	v_cvt_pk_bf16_f32 v99, v102, v103
	v_cvt_pk_bf16_f32 v100, v104, v105
	v_cvt_pk_bf16_f32 v101, v106, v107
	v_cvt_pk_bf16_f32 v102, v108, v109
	v_cvt_pk_bf16_f32 v103, v110, v111
	global_store_dwordx2 v11, v[96:97], s[56:57]
	global_store_dwordx2 v11, v[98:99], s[56:57] offset:512
	global_store_dwordx2 v11, v[100:101], s[56:57] offset:1024
	global_store_dwordx2 v11, v[102:103], s[56:57] offset:1536
	s_add_u32 s56, s56, 0x400000
	s_addc_u32 s57, s57, 0
	global_load_dwordx4 v[96:99], v6, s[36:37] nt
	global_load_dwordx4 v[100:103], v6, s[36:37] offset:1024 nt
	global_load_dwordx4 v[104:107], v6, s[36:37] offset:2048 nt
	global_load_dwordx4 v[108:111], v6, s[36:37] offset:3072 nt
	s_add_u32 s36, s36, 0x800000
	s_addc_u32 s37, s37, 0
	s_waitcnt vmcnt(22)
	v_pk_mul_f32 v[240:241], v[112:113], v[112:113]
	v_pk_mul_f32 v[242:243], v[120:121], v[120:121]
	v_pk_fma_f32 v[240:241], v[114:115], v[114:115], v[240:241]
	v_pk_fma_f32 v[242:243], v[122:123], v[122:123], v[242:243]
	v_pk_fma_f32 v[240:241], v[116:117], v[116:117], v[240:241]
	v_pk_fma_f32 v[242:243], v[124:125], v[124:125], v[242:243]
	v_pk_fma_f32 v[240:241], v[118:119], v[118:119], v[240:241]
	v_pk_fma_f32 v[242:243], v[126:127], v[126:127], v[242:243]
	v_pk_add_f32 v[240:241], v[240:241], v[242:243]
	s_nop 0
	v_add_f32_e32 v244, v240, v241
	s_nop 1
	v_add_f32_dpp v244, v244, v244 quad_perm:[1,0,3,2] row_mask:0xf bank_mask:0xf
	s_nop 1
	v_add_f32_dpp v244, v244, v244 quad_perm:[2,3,0,1] row_mask:0xf bank_mask:0xf
	s_nop 1
	v_add_f32_dpp v244, v244, v244 row_half_mirror row_mask:0xf bank_mask:0xf
	s_nop 1
	v_add_f32_dpp v244, v244, v244 row_mirror row_mask:0xf bank_mask:0xf
	s_nop 1
	v_readlane_b32 s38, v244, 0
	v_readlane_b32 s39, v244, 16
	v_readlane_b32 s40, v244, 32
	v_readlane_b32 s41, v244, 48
	s_nop 1
	v_mov_b32_e32 v246, s38
	v_add_f32_e32 v246, s39, v246
	v_add_f32_e32 v246, s40, v246
	v_add_f32_e32 v246, s41, v246
	v_fmamk_f32 v246, v246, 0x3a800000, v17
	v_rsq_f32_e32 v246, v246
	s_nop 0
	v_pk_mul_f32 v[112:113], v[112:113], v[246:247] op_sel_hi:[1,0]
	v_pk_mul_f32 v[114:115], v[114:115], v[246:247] op_sel_hi:[1,0]
	v_pk_mul_f32 v[116:117], v[116:117], v[246:247] op_sel_hi:[1,0]
	v_pk_mul_f32 v[118:119], v[118:119], v[246:247] op_sel_hi:[1,0]
	v_pk_mul_f32 v[120:121], v[120:121], v[246:247] op_sel_hi:[1,0]
	v_pk_mul_f32 v[122:123], v[122:123], v[246:247] op_sel_hi:[1,0]
	v_pk_mul_f32 v[124:125], v[124:125], v[246:247] op_sel_hi:[1,0]
	v_pk_mul_f32 v[126:127], v[126:127], v[246:247] op_sel_hi:[1,0]
	v_cvt_pk_bf16_f32 v112, v112, v113
	v_cvt_pk_bf16_f32 v113, v114, v115
	v_cvt_pk_bf16_f32 v114, v116, v117
	v_cvt_pk_bf16_f32 v115, v118, v119
	v_cvt_pk_bf16_f32 v116, v120, v121
	v_cvt_pk_bf16_f32 v117, v122, v123
	v_cvt_pk_bf16_f32 v118, v124, v125
	v_cvt_pk_bf16_f32 v119, v126, v127
	global_store_dwordx2 v11, v[112:113], s[56:57]
	global_store_dwordx2 v11, v[114:115], s[56:57] offset:512
	global_store_dwordx2 v11, v[116:117], s[56:57] offset:1024
	global_store_dwordx2 v11, v[118:119], s[56:57] offset:1536
	s_add_u32 s56, s56, 0x400000
	s_addc_u32 s57, s57, 0
	global_load_dwordx4 v[112:115], v6, s[36:37] nt
	global_load_dwordx4 v[116:119], v6, s[36:37] offset:1024 nt
	global_load_dwordx4 v[120:123], v6, s[36:37] offset:2048 nt
	global_load_dwordx4 v[124:127], v6, s[36:37] offset:3072 nt
	s_add_u32 s36, s36, 0x800000
	s_addc_u32 s37, s37, 0
	s_waitcnt vmcnt(26)
	v_pk_mul_f32 v[240:241], v[128:129], v[128:129]
	v_pk_mul_f32 v[242:243], v[136:137], v[136:137]
	v_pk_fma_f32 v[240:241], v[130:131], v[130:131], v[240:241]
	v_pk_fma_f32 v[242:243], v[138:139], v[138:139], v[242:243]
	v_pk_fma_f32 v[240:241], v[132:133], v[132:133], v[240:241]
	v_pk_fma_f32 v[242:243], v[140:141], v[140:141], v[242:243]
	v_pk_fma_f32 v[240:241], v[134:135], v[134:135], v[240:241]
	v_pk_fma_f32 v[242:243], v[142:143], v[142:143], v[242:243]
	v_pk_add_f32 v[240:241], v[240:241], v[242:243]
	s_nop 0
	v_add_f32_e32 v244, v240, v241
	s_nop 1
	v_add_f32_dpp v244, v244, v244 quad_perm:[1,0,3,2] row_mask:0xf bank_mask:0xf
	s_nop 1
	v_add_f32_dpp v244, v244, v244 quad_perm:[2,3,0,1] row_mask:0xf bank_mask:0xf
	s_nop 1
	v_add_f32_dpp v244, v244, v244 row_half_mirror row_mask:0xf bank_mask:0xf
	s_nop 1
	v_add_f32_dpp v244, v244, v244 row_mirror row_mask:0xf bank_mask:0xf
	s_nop 1
	v_readlane_b32 s38, v244, 0
	v_readlane_b32 s39, v244, 16
	v_readlane_b32 s40, v244, 32
	v_readlane_b32 s41, v244, 48
	s_nop 1
	v_mov_b32_e32 v246, s38
	v_add_f32_e32 v246, s39, v246
	v_add_f32_e32 v246, s40, v246
	v_add_f32_e32 v246, s41, v246
	v_fmamk_f32 v246, v246, 0x3a800000, v17
	v_rsq_f32_e32 v246, v246
	s_nop 0
	v_pk_mul_f32 v[128:129], v[128:129], v[246:247] op_sel_hi:[1,0]
	v_pk_mul_f32 v[130:131], v[130:131], v[246:247] op_sel_hi:[1,0]
	v_pk_mul_f32 v[132:133], v[132:133], v[246:247] op_sel_hi:[1,0]
	v_pk_mul_f32 v[134:135], v[134:135], v[246:247] op_sel_hi:[1,0]
	v_pk_mul_f32 v[136:137], v[136:137], v[246:247] op_sel_hi:[1,0]
	v_pk_mul_f32 v[138:139], v[138:139], v[246:247] op_sel_hi:[1,0]
	v_pk_mul_f32 v[140:141], v[140:141], v[246:247] op_sel_hi:[1,0]
	v_pk_mul_f32 v[142:143], v[142:143], v[246:247] op_sel_hi:[1,0]
	v_cvt_pk_bf16_f32 v128, v128, v129
	v_cvt_pk_bf16_f32 v129, v130, v131
	v_cvt_pk_bf16_f32 v130, v132, v133
	v_cvt_pk_bf16_f32 v131, v134, v135
	v_cvt_pk_bf16_f32 v132, v136, v137
	v_cvt_pk_bf16_f32 v133, v138, v139
	v_cvt_pk_bf16_f32 v134, v140, v141
	v_cvt_pk_bf16_f32 v135, v142, v143
	global_store_dwordx2 v11, v[128:129], s[56:57]
	global_store_dwordx2 v11, v[130:131], s[56:57] offset:512
	global_store_dwordx2 v11, v[132:133], s[56:57] offset:1024
	global_store_dwordx2 v11, v[134:135], s[56:57] offset:1536
	s_add_u32 s56, s56, 0x400000
	s_addc_u32 s57, s57, 0
	global_load_dwordx4 v[128:131], v6, s[36:37] nt
	global_load_dwordx4 v[132:135], v6, s[36:37] offset:1024 nt
	global_load_dwordx4 v[136:139], v6, s[36:37] offset:2048 nt
	global_load_dwordx4 v[140:143], v6, s[36:37] offset:3072 nt
	s_add_u32 s36, s36, 0x800000
	s_addc_u32 s37, s37, 0
	s_waitcnt vmcnt(16)
	v_pk_mul_f32 v[240:241], v[96:97], v[96:97]
	v_pk_mul_f32 v[242:243], v[104:105], v[104:105]
	v_pk_fma_f32 v[240:241], v[98:99], v[98:99], v[240:241]
	v_pk_fma_f32 v[242:243], v[106:107], v[106:107], v[242:243]
	v_pk_fma_f32 v[240:241], v[100:101], v[100:101], v[240:241]
	v_pk_fma_f32 v[242:243], v[108:109], v[108:109], v[242:243]
	v_pk_fma_f32 v[240:241], v[102:103], v[102:103], v[240:241]
	v_pk_fma_f32 v[242:243], v[110:111], v[110:111], v[242:243]
	v_pk_add_f32 v[240:241], v[240:241], v[242:243]
	s_nop 0
	v_add_f32_e32 v244, v240, v241
	s_nop 1
	v_add_f32_dpp v244, v244, v244 quad_perm:[1,0,3,2] row_mask:0xf bank_mask:0xf
	s_nop 1
	v_add_f32_dpp v244, v244, v244 quad_perm:[2,3,0,1] row_mask:0xf bank_mask:0xf
	s_nop 1
	v_add_f32_dpp v244, v244, v244 row_half_mirror row_mask:0xf bank_mask:0xf
	s_nop 1
	v_add_f32_dpp v244, v244, v244 row_mirror row_mask:0xf bank_mask:0xf
	s_nop 1
	v_readlane_b32 s38, v244, 0
	v_readlane_b32 s39, v244, 16
	v_readlane_b32 s40, v244, 32
	v_readlane_b32 s41, v244, 48
	s_nop 1
	v_mov_b32_e32 v246, s38
	v_add_f32_e32 v246, s39, v246
	v_add_f32_e32 v246, s40, v246
	v_add_f32_e32 v246, s41, v246
	v_fmamk_f32 v246, v246, 0x3a800000, v17
	v_rsq_f32_e32 v246, v246
	s_nop 0
	v_pk_mul_f32 v[96:97], v[96:97], v[246:247] op_sel_hi:[1,0]
	v_pk_mul_f32 v[98:99], v[98:99], v[246:247] op_sel_hi:[1,0]
	v_pk_mul_f32 v[100:101], v[100:101], v[246:247] op_sel_hi:[1,0]
	v_pk_mul_f32 v[102:103], v[102:103], v[246:247] op_sel_hi:[1,0]
	v_pk_mul_f32 v[104:105], v[104:105], v[246:247] op_sel_hi:[1,0]
	v_pk_mul_f32 v[106:107], v[106:107], v[246:247] op_sel_hi:[1,0]
	v_pk_mul_f32 v[108:109], v[108:109], v[246:247] op_sel_hi:[1,0]
	v_pk_mul_f32 v[110:111], v[110:111], v[246:247] op_sel_hi:[1,0]
	v_cvt_pk_bf16_f32 v96, v96, v97
	v_cvt_pk_bf16_f32 v97, v98, v99
	v_cvt_pk_bf16_f32 v98, v100, v101
	v_cvt_pk_bf16_f32 v99, v102, v103
	v_cvt_pk_bf16_f32 v100, v104, v105
	v_cvt_pk_bf16_f32 v101, v106, v107
	v_cvt_pk_bf16_f32 v102, v108, v109
	v_cvt_pk_bf16_f32 v103, v110, v111
	global_store_dwordx2 v11, v[96:97], s[56:57]
	global_store_dwordx2 v11, v[98:99], s[56:57] offset:512
	global_store_dwordx2 v11, v[100:101], s[56:57] offset:1024
	global_store_dwordx2 v11, v[102:103], s[56:57] offset:1536
	s_add_u32 s56, s56, 0x400000
	s_addc_u32 s57, s57, 0
	global_load_dwordx4 v[96:99], v6, s[36:37] nt
	global_load_dwordx4 v[100:103], v6, s[36:37] offset:1024 nt
	global_load_dwordx4 v[104:107], v6, s[36:37] offset:2048 nt
	global_load_dwordx4 v[108:111], v6, s[36:37] offset:3072 nt
	s_add_u32 s36, s36, 0x800000
	s_addc_u32 s37, s37, 0
	s_waitcnt vmcnt(16)
	v_pk_mul_f32 v[240:241], v[112:113], v[112:113]
	v_pk_mul_f32 v[242:243], v[120:121], v[120:121]
	v_pk_fma_f32 v[240:241], v[114:115], v[114:115], v[240:241]
	v_pk_fma_f32 v[242:243], v[122:123], v[122:123], v[242:243]
	v_pk_fma_f32 v[240:241], v[116:117], v[116:117], v[240:241]
	v_pk_fma_f32 v[242:243], v[124:125], v[124:125], v[242:243]
	v_pk_fma_f32 v[240:241], v[118:119], v[118:119], v[240:241]
	v_pk_fma_f32 v[242:243], v[126:127], v[126:127], v[242:243]
	v_pk_add_f32 v[240:241], v[240:241], v[242:243]
	s_nop 0
	v_add_f32_e32 v244, v240, v241
	s_nop 1
	v_add_f32_dpp v244, v244, v244 quad_perm:[1,0,3,2] row_mask:0xf bank_mask:0xf
	s_nop 1
	v_add_f32_dpp v244, v244, v244 quad_perm:[2,3,0,1] row_mask:0xf bank_mask:0xf
	s_nop 1
	v_add_f32_dpp v244, v244, v244 row_half_mirror row_mask:0xf bank_mask:0xf
	s_nop 1
	v_add_f32_dpp v244, v244, v244 row_mirror row_mask:0xf bank_mask:0xf
	s_nop 1
	v_readlane_b32 s38, v244, 0
	v_readlane_b32 s39, v244, 16
	v_readlane_b32 s40, v244, 32
	v_readlane_b32 s41, v244, 48
	s_nop 1
	v_mov_b32_e32 v246, s38
	v_add_f32_e32 v246, s39, v246
	v_add_f32_e32 v246, s40, v246
	v_add_f32_e32 v246, s41, v246
	v_fmamk_f32 v246, v246, 0x3a800000, v17
	v_rsq_f32_e32 v246, v246
	s_nop 0
	v_pk_mul_f32 v[112:113], v[112:113], v[246:247] op_sel_hi:[1,0]
	v_pk_mul_f32 v[114:115], v[114:115], v[246:247] op_sel_hi:[1,0]
	v_pk_mul_f32 v[116:117], v[116:117], v[246:247] op_sel_hi:[1,0]
	v_pk_mul_f32 v[118:119], v[118:119], v[246:247] op_sel_hi:[1,0]
	v_pk_mul_f32 v[120:121], v[120:121], v[246:247] op_sel_hi:[1,0]
	v_pk_mul_f32 v[122:123], v[122:123], v[246:247] op_sel_hi:[1,0]
	v_pk_mul_f32 v[124:125], v[124:125], v[246:247] op_sel_hi:[1,0]
	v_pk_mul_f32 v[126:127], v[126:127], v[246:247] op_sel_hi:[1,0]
	v_cvt_pk_bf16_f32 v112, v112, v113
	v_cvt_pk_bf16_f32 v113, v114, v115
	v_cvt_pk_bf16_f32 v114, v116, v117
	v_cvt_pk_bf16_f32 v115, v118, v119
	v_cvt_pk_bf16_f32 v116, v120, v121
	v_cvt_pk_bf16_f32 v117, v122, v123
	v_cvt_pk_bf16_f32 v118, v124, v125
	v_cvt_pk_bf16_f32 v119, v126, v127
	global_store_dwordx2 v11, v[112:113], s[56:57]
	global_store_dwordx2 v11, v[114:115], s[56:57] offset:512
	global_store_dwordx2 v11, v[116:117], s[56:57] offset:1024
	global_store_dwordx2 v11, v[118:119], s[56:57] offset:1536
	s_add_u32 s56, s56, 0x400000
	s_addc_u32 s57, s57, 0
	global_load_dwordx4 v[112:115], v6, s[36:37] nt
	global_load_dwordx4 v[116:119], v6, s[36:37] offset:1024 nt
	global_load_dwordx4 v[120:123], v6, s[36:37] offset:2048 nt
	global_load_dwordx4 v[124:127], v6, s[36:37] offset:3072 nt
	s_waitcnt vmcnt(16)
	v_pk_mul_f32 v[240:241], v[128:129], v[128:129]
	v_pk_mul_f32 v[242:243], v[136:137], v[136:137]
	v_pk_fma_f32 v[240:241], v[130:131], v[130:131], v[240:241]
	v_pk_fma_f32 v[242:243], v[138:139], v[138:139], v[242:243]
	v_pk_fma_f32 v[240:241], v[132:133], v[132:133], v[240:241]
	v_pk_fma_f32 v[242:243], v[140:141], v[140:141], v[242:243]
	v_pk_fma_f32 v[240:241], v[134:135], v[134:135], v[240:241]
	v_pk_fma_f32 v[242:243], v[142:143], v[142:143], v[242:243]
	v_pk_add_f32 v[240:241], v[240:241], v[242:243]
	s_nop 0
	v_add_f32_e32 v244, v240, v241
	s_nop 1
	v_add_f32_dpp v244, v244, v244 quad_perm:[1,0,3,2] row_mask:0xf bank_mask:0xf
	s_nop 1
	v_add_f32_dpp v244, v244, v244 quad_perm:[2,3,0,1] row_mask:0xf bank_mask:0xf
	s_nop 1
	v_add_f32_dpp v244, v244, v244 row_half_mirror row_mask:0xf bank_mask:0xf
	s_nop 1
	v_add_f32_dpp v244, v244, v244 row_mirror row_mask:0xf bank_mask:0xf
	s_nop 1
	v_readlane_b32 s38, v244, 0
	v_readlane_b32 s39, v244, 16
	v_readlane_b32 s40, v244, 32
	v_readlane_b32 s41, v244, 48
	s_nop 1
	v_mov_b32_e32 v246, s38
	v_add_f32_e32 v246, s39, v246
	v_add_f32_e32 v246, s40, v246
	v_add_f32_e32 v246, s41, v246
	v_fmamk_f32 v246, v246, 0x3a800000, v17
	v_rsq_f32_e32 v246, v246
	s_nop 0
	v_pk_mul_f32 v[128:129], v[128:129], v[246:247] op_sel_hi:[1,0]
	v_pk_mul_f32 v[130:131], v[130:131], v[246:247] op_sel_hi:[1,0]
	v_pk_mul_f32 v[132:133], v[132:133], v[246:247] op_sel_hi:[1,0]
	v_pk_mul_f32 v[134:135], v[134:135], v[246:247] op_sel_hi:[1,0]
	v_pk_mul_f32 v[136:137], v[136:137], v[246:247] op_sel_hi:[1,0]
	v_pk_mul_f32 v[138:139], v[138:139], v[246:247] op_sel_hi:[1,0]
	v_pk_mul_f32 v[140:141], v[140:141], v[246:247] op_sel_hi:[1,0]
	v_pk_mul_f32 v[142:143], v[142:143], v[246:247] op_sel_hi:[1,0]
	v_cvt_pk_bf16_f32 v128, v128, v129
	v_cvt_pk_bf16_f32 v129, v130, v131
	v_cvt_pk_bf16_f32 v130, v132, v133
	v_cvt_pk_bf16_f32 v131, v134, v135
	v_cvt_pk_bf16_f32 v132, v136, v137
	v_cvt_pk_bf16_f32 v133, v138, v139
	v_cvt_pk_bf16_f32 v134, v140, v141
	v_cvt_pk_bf16_f32 v135, v142, v143
	global_store_dwordx2 v11, v[128:129], s[56:57]
	global_store_dwordx2 v11, v[130:131], s[56:57] offset:512
	global_store_dwordx2 v11, v[132:133], s[56:57] offset:1024
	global_store_dwordx2 v11, v[134:135], s[56:57] offset:1536
	s_add_u32 s56, s56, 0x400000
	s_addc_u32 s57, s57, 0
	s_waitcnt vmcnt(12)
	v_pk_mul_f32 v[240:241], v[96:97], v[96:97]
	v_pk_mul_f32 v[242:243], v[104:105], v[104:105]
	v_pk_fma_f32 v[240:241], v[98:99], v[98:99], v[240:241]
	v_pk_fma_f32 v[242:243], v[106:107], v[106:107], v[242:243]
	v_pk_fma_f32 v[240:241], v[100:101], v[100:101], v[240:241]
	v_pk_fma_f32 v[242:243], v[108:109], v[108:109], v[242:243]
	v_pk_fma_f32 v[240:241], v[102:103], v[102:103], v[240:241]
	v_pk_fma_f32 v[242:243], v[110:111], v[110:111], v[242:243]
	v_pk_add_f32 v[240:241], v[240:241], v[242:243]
	s_nop 0
	v_add_f32_e32 v244, v240, v241
	s_nop 1
	v_add_f32_dpp v244, v244, v244 quad_perm:[1,0,3,2] row_mask:0xf bank_mask:0xf
	s_nop 1
	v_add_f32_dpp v244, v244, v244 quad_perm:[2,3,0,1] row_mask:0xf bank_mask:0xf
	s_nop 1
	v_add_f32_dpp v244, v244, v244 row_half_mirror row_mask:0xf bank_mask:0xf
	s_nop 1
	v_add_f32_dpp v244, v244, v244 row_mirror row_mask:0xf bank_mask:0xf
	s_nop 1
	v_readlane_b32 s38, v244, 0
	v_readlane_b32 s39, v244, 16
	v_readlane_b32 s40, v244, 32
	v_readlane_b32 s41, v244, 48
	s_nop 1
	v_mov_b32_e32 v246, s38
	v_add_f32_e32 v246, s39, v246
	v_add_f32_e32 v246, s40, v246
	v_add_f32_e32 v246, s41, v246
	v_fmamk_f32 v246, v246, 0x3a800000, v17
	v_rsq_f32_e32 v246, v246
	s_nop 0
	v_pk_mul_f32 v[96:97], v[96:97], v[246:247] op_sel_hi:[1,0]
	v_pk_mul_f32 v[98:99], v[98:99], v[246:247] op_sel_hi:[1,0]
	v_pk_mul_f32 v[100:101], v[100:101], v[246:247] op_sel_hi:[1,0]
	v_pk_mul_f32 v[102:103], v[102:103], v[246:247] op_sel_hi:[1,0]
	v_pk_mul_f32 v[104:105], v[104:105], v[246:247] op_sel_hi:[1,0]
	v_pk_mul_f32 v[106:107], v[106:107], v[246:247] op_sel_hi:[1,0]
	v_pk_mul_f32 v[108:109], v[108:109], v[246:247] op_sel_hi:[1,0]
	v_pk_mul_f32 v[110:111], v[110:111], v[246:247] op_sel_hi:[1,0]
	v_cvt_pk_bf16_f32 v96, v96, v97
	v_cvt_pk_bf16_f32 v97, v98, v99
	v_cvt_pk_bf16_f32 v98, v100, v101
	v_cvt_pk_bf16_f32 v99, v102, v103
	v_cvt_pk_bf16_f32 v100, v104, v105
	v_cvt_pk_bf16_f32 v101, v106, v107
	v_cvt_pk_bf16_f32 v102, v108, v109
	v_cvt_pk_bf16_f32 v103, v110, v111
	global_store_dwordx2 v11, v[96:97], s[56:57]
	global_store_dwordx2 v11, v[98:99], s[56:57] offset:512
	global_store_dwordx2 v11, v[100:101], s[56:57] offset:1024
	global_store_dwordx2 v11, v[102:103], s[56:57] offset:1536
	s_add_u32 s56, s56, 0x400000
	s_addc_u32 s57, s57, 0
	s_waitcnt vmcnt(8)
	v_pk_mul_f32 v[240:241], v[112:113], v[112:113]
	v_pk_mul_f32 v[242:243], v[120:121], v[120:121]
	v_pk_fma_f32 v[240:241], v[114:115], v[114:115], v[240:241]
	v_pk_fma_f32 v[242:243], v[122:123], v[122:123], v[242:243]
	v_pk_fma_f32 v[240:241], v[116:117], v[116:117], v[240:241]
	v_pk_fma_f32 v[242:243], v[124:125], v[124:125], v[242:243]
	v_pk_fma_f32 v[240:241], v[118:119], v[118:119], v[240:241]
	v_pk_fma_f32 v[242:243], v[126:127], v[126:127], v[242:243]
	v_pk_add_f32 v[240:241], v[240:241], v[242:243]
	s_nop 0
	v_add_f32_e32 v244, v240, v241
	s_nop 1
	v_add_f32_dpp v244, v244, v244 quad_perm:[1,0,3,2] row_mask:0xf bank_mask:0xf
	s_nop 1
	v_add_f32_dpp v244, v244, v244 quad_perm:[2,3,0,1] row_mask:0xf bank_mask:0xf
	s_nop 1
	v_add_f32_dpp v244, v244, v244 row_half_mirror row_mask:0xf bank_mask:0xf
	s_nop 1
	v_add_f32_dpp v244, v244, v244 row_mirror row_mask:0xf bank_mask:0xf
	s_nop 1
	v_readlane_b32 s38, v244, 0
	v_readlane_b32 s39, v244, 16
	v_readlane_b32 s40, v244, 32
	v_readlane_b32 s41, v244, 48
	s_nop 1
	v_mov_b32_e32 v246, s38
	v_add_f32_e32 v246, s39, v246
	v_add_f32_e32 v246, s40, v246
	v_add_f32_e32 v246, s41, v246
	v_fmamk_f32 v246, v246, 0x3a800000, v17
	v_rsq_f32_e32 v246, v246
	s_nop 0
	v_pk_mul_f32 v[112:113], v[112:113], v[246:247] op_sel_hi:[1,0]
	v_pk_mul_f32 v[114:115], v[114:115], v[246:247] op_sel_hi:[1,0]
	v_pk_mul_f32 v[116:117], v[116:117], v[246:247] op_sel_hi:[1,0]
	v_pk_mul_f32 v[118:119], v[118:119], v[246:247] op_sel_hi:[1,0]
	v_pk_mul_f32 v[120:121], v[120:121], v[246:247] op_sel_hi:[1,0]
	v_pk_mul_f32 v[122:123], v[122:123], v[246:247] op_sel_hi:[1,0]
	v_pk_mul_f32 v[124:125], v[124:125], v[246:247] op_sel_hi:[1,0]
	v_pk_mul_f32 v[126:127], v[126:127], v[246:247] op_sel_hi:[1,0]
	v_cvt_pk_bf16_f32 v112, v112, v113
	v_cvt_pk_bf16_f32 v113, v114, v115
	v_cvt_pk_bf16_f32 v114, v116, v117
	v_cvt_pk_bf16_f32 v115, v118, v119
	v_cvt_pk_bf16_f32 v116, v120, v121
	v_cvt_pk_bf16_f32 v117, v122, v123
	v_cvt_pk_bf16_f32 v118, v124, v125
	v_cvt_pk_bf16_f32 v119, v126, v127
	global_store_dwordx2 v11, v[112:113], s[56:57]
	global_store_dwordx2 v11, v[114:115], s[56:57] offset:512
	global_store_dwordx2 v11, v[116:117], s[56:57] offset:1024
	global_store_dwordx2 v11, v[118:119], s[56:57] offset:1536
.Lprep_done:
	s_mov_b32 s100, 0x440000
	s_movk_i32 s101, 0x880
	s_branch .LBB0_45
.Lprep_old:
	s_cmpk_gt_i32 s2, 0x4bf
	s_cbranch_scc1 .LBB0_45
	s_cmpk_gt_i32 s2, 0x43f
	s_cselect_b64 s[8:9], -1, 0
	s_movk_i32 s3, 0x50
	s_and_b64 s[4:5], s[8:9], exec
	s_cselect_b32 s3, s3, 0x68
	s_cmpk_lt_i32 s2, 0x340
	s_cselect_b64 s[10:11], -1, 0
	s_and_b64 s[4:5], s[10:11], exec
	s_cselect_b32 s3, 24, s3
	s_add_u32 s4, s0, s3
	s_addc_u32 s5, s1, 0
	s_load_dwordx2 s[4:5], s[4:5], 0x0
	s_add_i32 s3, s2, 0xfffffbc0
	s_cmp_gt_u32 s3, 0xfffffeff
	s_mov_b64 s[6:7], 0
	s_cbranch_scc1 .LBB0_8
	s_and_b64 s[6:7], s[10:11], exec
	s_cselect_b32 s3, 16, 0x48
	s_add_u32 s6, s0, s3
	s_addc_u32 s7, s1, 0
	s_load_dwordx2 s[6:7], s[6:7], 0x0

.LBB0_45:
	s_add_i32 s3, s2, 0x4c0
	s_add_i32 s3, s3, s101
	s_cmpk_gt_i32 s3, 0xd60
	v_lshlrev_b32_e32 v234, 2, v0
	v_mbcnt_lo_u32_b32 v176, -1, 0
	s_cbranch_scc1 .LBB0_59
	s_load_dword s25, s[0:1], 0xf0
	s_load_dwordx4 s[12:15], s[0:1], 0x0
	s_load_dwordx2 s[10:11], s[0:1], 0x28
	s_load_dwordx4 s[28:31], s[0:1], 0x38
	s_load_dwordx4 s[36:39], s[0:1], 0x58
	s_load_dwordx2 s[20:21], s[0:1], 0xa0
	s_load_dwordx4 s[16:19], s[0:1], 0x90
	s_load_dwordx2 s[22:23], s[0:1], 0xd8
	v_mov_b32_e32 v5, 0
	v_lshlrev_b32_e32 v4, 2, v2
	s_waitcnt lgkmcnt(0)
	v_lshl_add_u64 v[6:7], s[28:29], 0, v[4:5]
	v_lshl_add_u64 v[8:9], s[30:31], 0, v[4:5]
	s_waitcnt vmcnt(4)
	v_lshl_add_u64 v[10:11], s[36:37], 0, v[4:5]
	v_lshl_add_u64 v[12:13], s[38:39], 0, v[4:5]
	v_lshl_or_b32 v4, s2, 11, v234
	v_mbcnt_hi_u32_b32 v20, -1, v176
	v_and_b32_e32 v1, 0x7c, v234
	v_add_u32_e32 v14, 0xffbc0000, v4
	v_add_u32_e32 v14, s100, v14
	v_and_b32_e32 v4, 64, v20
	v_or_b32_e32 v3, 2, v1
	v_or_b32_e32 v17, 3, v1
	v_cmp_gt_u32_e64 s[4:5], 64, v0
	v_cmp_eq_u32_e64 s[6:7], 0, v2
	s_lshl_b32 s27, s25, 11
	v_lshl_or_b32 v18, s2, 3, v16
	s_lshl_b32 s28, s25, 3
	s_mov_b32 s24, 0x41000000
	s_mov_b32 s26, 0x3fb8aa3b
	s_movk_i32 s29, 0x4000
	v_mov_b32_e32 v19, 0x358637bd
	s_mov_b32 s30, 0x800000
	v_add_u32_e32 v21, 64, v4
	v_xor_b32_e32 v22, 32, v20
	v_xor_b32_e32 v23, 16, v20
	v_xor_b32_e32 v24, 8, v20
	v_xor_b32_e32 v25, 4, v20
	v_xor_b32_e32 v26, 2, v20
	v_xor_b32_e32 v27, 1, v20
	s_branch .LBB0_48

	.amdhsa_kernel _Z10fwd_kernel6Paramsi
		.amdhsa_group_segment_fixed_size 16
		.amdhsa_private_segment_fixed_size 0
		.amdhsa_kernarg_size 496
		.amdhsa_user_sgpr_count 2
		.amdhsa_user_sgpr_dispatch_ptr 0
		.amdhsa_user_sgpr_queue_ptr 0
		.amdhsa_user_sgpr_kernarg_segment_ptr 1
		.amdhsa_user_sgpr_dispatch_id 0
		.amdhsa_user_sgpr_kernarg_preload_length 0
		.amdhsa_user_sgpr_kernarg_preload_offset 0
		.amdhsa_user_sgpr_private_segment_size 0
		.amdhsa_uses_dynamic_stack 0
		.amdhsa_enable_private_segment 0
		.amdhsa_system_sgpr_workgroup_id_x 1
		.amdhsa_system_sgpr_workgroup_id_y 0
		.amdhsa_system_sgpr_workgroup_id_z 0
		.amdhsa_system_sgpr_workgroup_info 0
		.amdhsa_system_vgpr_workitem_id 0
		.amdhsa_next_free_vgpr 256
		.amdhsa_next_free_sgpr 102
		.amdhsa_accum_offset 256
		.amdhsa_reserve_vcc 1
		.amdhsa_float_round_mode_32 0
		.amdhsa_float_round_mode_16_64 0
		.amdhsa_float_denorm_mode_32 3
		.amdhsa_float_denorm_mode_16_64 3
		.amdhsa_dx10_clamp 1
		.amdhsa_ieee_mode 1
		.amdhsa_fp16_overflow 0
		.amdhsa_tg_split 0
		.amdhsa_exception_fp_ieee_invalid_op 0
		.amdhsa_exception_fp_denorm_src 0
		.amdhsa_exception_fp_ieee_div_zero 0
		.amdhsa_exception_fp_ieee_overflow 0
		.amdhsa_exception_fp_ieee_underflow 0
		.amdhsa_exception_fp_ieee_inexact 0
		.amdhsa_exception_int_div_zero 0
	.end_amdhsa_kernel

.Lfunc_end0:
	.size	_Z10fwd_kernel6Paramsi, .Lfunc_end0-_Z10fwd_kernel6Paramsi
	.set _Z10fwd_kernel6Paramsi.num_vgpr, 256
	.set _Z10fwd_kernel6Paramsi.num_agpr, 0
	.set _Z10fwd_kernel6Paramsi.numbered_sgpr, 102
	.set _Z10fwd_kernel6Paramsi.num_named_barrier, 0
	.set _Z10fwd_kernel6Paramsi.private_seg_size, 0
	.set _Z10fwd_kernel6Paramsi.uses_vcc, 1
	.set _Z10fwd_kernel6Paramsi.uses_flat_scratch, 0
	.set _Z10fwd_kernel6Paramsi.has_dyn_sized_stack, 0
	.set _Z10fwd_kernel6Paramsi.has_recursion, 0
	.set _Z10fwd_kernel6Paramsi.has_indirect_call, 0

amdhsa.kernels:
  - .agpr_count:     0
    .args:
      - .offset:         0
        .size:           232
        .value_kind:     by_value
      - .offset:         232
        .size:           4
        .value_kind:     by_value
      - .offset:         240
        .size:           4
        .value_kind:     hidden_block_count_x
      - .offset:         244
        .size:           4
        .value_kind:     hidden_block_count_y
      - .offset:         248
        .size:           4
        .value_kind:     hidden_block_count_z
      - .offset:         252
        .size:           2
        .value_kind:     hidden_group_size_x
      - .offset:         254
        .size:           2
        .value_kind:     hidden_group_size_y
      - .offset:         256
        .size:           2
        .value_kind:     hidden_group_size_z
      - .offset:         258
        .size:           2
        .value_kind:     hidden_remainder_x
      - .offset:         260
        .size:           2
        .value_kind:     hidden_remainder_y
      - .offset:         262
        .size:           2
        .value_kind:     hidden_remainder_z
      - .offset:         280
        .size:           8
        .value_kind:     hidden_global_offset_x
      - .offset:         288
        .size:           8
        .value_kind:     hidden_global_offset_y
      - .offset:         296
        .size:           8
        .value_kind:     hidden_global_offset_z
      - .offset:         304
        .size:           2
        .value_kind:     hidden_grid_dims
      - .offset:         360
        .size:           4
        .value_kind:     hidden_dynamic_lds_size
    .group_segment_fixed_size: 16
    .kernarg_segment_align: 8
    .kernarg_segment_size: 496
    .language:       OpenCL C
    .language_version:
      - 2
      - 0
    .max_flat_workgroup_size: 512
    .name:           _Z10fwd_kernel6Paramsi
    .private_segment_fixed_size: 0
    .sgpr_count:     108
    .sgpr_spill_count: 52
    .symbol:         _Z10fwd_kernel6Paramsi.kd
    .uniform_work_group_size: 1
    .uses_dynamic_stack: false
    .vgpr_count:     256
    .vgpr_spill_count: 0
    .wavefront_size: 64
